# out-proj epilogues (layers 0-2) rewritten: all 16 residual loads issued up front, params loaded once, counted waits
# speedup vs baseline: 1.0570x; 1.0134x over previous
.LBB0_463:
	s_add_i32 s42, s43, 2
	s_setprio 1
	ds_read_b128 v[126:129], v120 offset:32768
	ds_read_b128 v[134:137], v120 offset:34816
	ds_read_b128 v[130:133], v119
	ds_read_b128 v[138:141], v119 offset:2048
	ds_read_b128 v[164:167], v119 offset:4096
	ds_read_b128 v[168:171], v119 offset:6144
	s_waitcnt lgkmcnt(3)
	v_mfma_f32_16x16x32_bf16 v[60:63], v[126:129], v[130:133], v[60:63]
	ds_read_b128 v[172:175], v120 offset:36864
	v_mfma_f32_16x16x32_bf16 v[40:43], v[134:137], v[130:133], v[40:43]
	ds_read_b128 v[176:179], v120 offset:38912
	s_waitcnt lgkmcnt(1)
	v_mfma_f32_16x16x32_bf16 v[28:31], v[172:175], v[130:133], v[28:31]
	s_waitcnt lgkmcnt(0)
	v_mfma_f32_16x16x32_bf16 v[12:15], v[176:179], v[130:133], v[12:15]
	s_add_u32 m0, s44, 0x4000
	s_nop 0
	global_load_lds_dwordx4 v68, s[98:99]
	ds_read_b128 v[180:183], v121
	v_mfma_f32_16x16x32_bf16 v[56:59], v[126:129], v[138:141], v[56:59]
	v_mfma_f32_16x16x32_bf16 v[44:47], v[134:137], v[138:141], v[44:47]
	s_add_u32 m0, s44, 0x5000
	s_nop 0
	global_load_lds_dwordx4 v69, s[98:99]
	ds_read_b128 v[188:191], v121 offset:2048
	v_mfma_f32_16x16x32_bf16 v[24:27], v[172:175], v[138:141], v[24:27]
	v_mfma_f32_16x16x32_bf16 v[8:11], v[176:179], v[138:141], v[8:11]
	s_add_u32 m0, s44, 0x6000
	s_nop 0
	global_load_lds_dwordx4 v70, s[98:99]
	ds_read_b128 v[192:195], v121 offset:4096
	v_mfma_f32_16x16x32_bf16 v[52:55], v[126:129], v[164:167], v[52:55]
	v_mfma_f32_16x16x32_bf16 v[36:39], v[134:137], v[164:167], v[36:39]
	s_add_u32 m0, s44, 0x7000
	s_nop 0
	global_load_lds_dwordx4 v71, s[98:99]
	ds_read_b128 v[200:203], v121 offset:6144
	v_mfma_f32_16x16x32_bf16 v[20:23], v[172:175], v[164:167], v[20:23]
	v_mfma_f32_16x16x32_bf16 v[4:7], v[176:179], v[164:167], v[4:7]
	s_add_u32 m0, s44, 0xc000
	s_nop 0
	global_load_lds_dwordx4 v68, s[100:101]
	ds_read_b128 v[204:207], v122 offset:32768
	v_mfma_f32_16x16x32_bf16 v[48:51], v[126:129], v[168:171], v[48:51]
	v_mfma_f32_16x16x32_bf16 v[32:35], v[134:137], v[168:171], v[32:35]
	s_add_u32 m0, s44, 0xd000
	s_nop 0
	global_load_lds_dwordx4 v69, s[100:101]
	ds_read_b128 v[134:137], v122 offset:34816
	v_mfma_f32_16x16x32_bf16 v[16:19], v[172:175], v[168:171], v[16:19]
	v_mfma_f32_16x16x32_bf16 v[0:3], v[176:179], v[168:171], v[0:3]
	s_add_u32 m0, s44, 0xe000
	s_nop 0
	global_load_lds_dwordx4 v70, s[100:101]
	ds_read_b128 v[172:175], v122 offset:36864
	s_waitcnt lgkmcnt(2)
	v_mfma_f32_16x16x32_bf16 v[60:63], v[204:207], v[180:183], v[60:63]
	s_waitcnt lgkmcnt(1)
	v_mfma_f32_16x16x32_bf16 v[40:43], v[134:137], v[180:183], v[40:43]
	s_add_u32 m0, s44, 0xf000
	s_nop 0
	global_load_lds_dwordx4 v71, s[100:101]
	s_add_u32 s98, s98, 0x80
	s_addc_u32 s99, s99, 0
	s_add_u32 s100, s100, 0x80
	s_addc_u32 s101, s101, 0
	ds_read_b128 v[208:211], v122 offset:38912
	s_waitcnt lgkmcnt(1)
	v_mfma_f32_16x16x32_bf16 v[28:31], v[172:175], v[180:183], v[28:31]
	s_waitcnt lgkmcnt(0)
	v_mfma_f32_16x16x32_bf16 v[12:15], v[208:211], v[180:183], v[12:15]
	v_mfma_f32_16x16x32_bf16 v[56:59], v[204:207], v[188:191], v[56:59]
	v_mfma_f32_16x16x32_bf16 v[44:47], v[134:137], v[188:191], v[44:47]
	v_mfma_f32_16x16x32_bf16 v[24:27], v[172:175], v[188:191], v[24:27]
	v_mfma_f32_16x16x32_bf16 v[8:11], v[208:211], v[188:191], v[8:11]
	v_mfma_f32_16x16x32_bf16 v[52:55], v[204:207], v[192:195], v[52:55]
	v_mfma_f32_16x16x32_bf16 v[36:39], v[134:137], v[192:195], v[36:39]
	v_mfma_f32_16x16x32_bf16 v[20:23], v[172:175], v[192:195], v[20:23]
	v_mfma_f32_16x16x32_bf16 v[4:7], v[208:211], v[192:195], v[4:7]
	v_mfma_f32_16x16x32_bf16 v[48:51], v[204:207], v[200:203], v[48:51]
	v_mfma_f32_16x16x32_bf16 v[32:35], v[134:137], v[200:203], v[32:35]
	v_mfma_f32_16x16x32_bf16 v[16:19], v[172:175], v[200:203], v[16:19]
	v_mfma_f32_16x16x32_bf16 v[0:3], v[208:211], v[200:203], v[0:3]
	s_setprio 0
	s_waitcnt vmcnt(0) lgkmcnt(0)
	s_barrier
	s_setprio 1
	ds_read_b128 v[84:87], v120 offset:49152
	ds_read_b128 v[88:91], v120 offset:51200
	ds_read_b128 v[64:67], v119 offset:16384
	ds_read_b128 v[72:75], v119 offset:18432
	ds_read_b128 v[76:79], v119 offset:20480
	ds_read_b128 v[92:95], v119 offset:22528
	s_waitcnt lgkmcnt(3)
	v_mfma_f32_16x16x32_bf16 v[60:63], v[84:87], v[64:67], v[60:63]
	ds_read_b128 v[134:137], v120 offset:53248
	v_mfma_f32_16x16x32_bf16 v[40:43], v[88:91], v[64:67], v[40:43]
	ds_read_b128 v[172:175], v120 offset:55296
	s_waitcnt lgkmcnt(1)
	v_mfma_f32_16x16x32_bf16 v[28:31], v[134:137], v[64:67], v[28:31]
	s_waitcnt lgkmcnt(0)
	v_mfma_f32_16x16x32_bf16 v[12:15], v[172:175], v[64:67], v[12:15]
	s_add_u32 m0, s44, 0x0
	s_nop 0
	global_load_lds_dwordx4 v68, s[98:99]
	ds_read_b128 v[180:183], v121 offset:16384
	v_mfma_f32_16x16x32_bf16 v[56:59], v[84:87], v[72:75], v[56:59]
	v_mfma_f32_16x16x32_bf16 v[44:47], v[88:91], v[72:75], v[44:47]
	s_add_u32 m0, s44, 0x1000
	s_nop 0
	global_load_lds_dwordx4 v69, s[98:99]
	ds_read_b128 v[188:191], v121 offset:18432
	v_mfma_f32_16x16x32_bf16 v[24:27], v[134:137], v[72:75], v[24:27]
	v_mfma_f32_16x16x32_bf16 v[8:11], v[172:175], v[72:75], v[8:11]
	s_add_u32 m0, s44, 0x2000
	s_nop 0
	global_load_lds_dwordx4 v70, s[98:99]
	ds_read_b128 v[192:195], v121 offset:20480
	v_mfma_f32_16x16x32_bf16 v[52:55], v[84:87], v[76:79], v[52:55]
	v_mfma_f32_16x16x32_bf16 v[36:39], v[88:91], v[76:79], v[36:39]
	s_add_u32 m0, s44, 0x3000
	s_nop 0
	global_load_lds_dwordx4 v71, s[98:99]
	ds_read_b128 v[200:203], v121 offset:22528
	v_mfma_f32_16x16x32_bf16 v[20:23], v[134:137], v[76:79], v[20:23]
	v_mfma_f32_16x16x32_bf16 v[4:7], v[172:175], v[76:79], v[4:7]
	s_add_u32 m0, s44, 0x8000
	s_nop 0
	global_load_lds_dwordx4 v68, s[100:101]
	ds_read_b128 v[204:207], v122 offset:49152
	v_mfma_f32_16x16x32_bf16 v[48:51], v[84:87], v[92:95], v[48:51]
	v_mfma_f32_16x16x32_bf16 v[32:35], v[88:91], v[92:95], v[32:35]
	s_add_u32 m0, s44, 0x9000
	s_nop 0
	global_load_lds_dwordx4 v69, s[100:101]
	ds_read_b128 v[208:211], v122 offset:51200
	v_mfma_f32_16x16x32_bf16 v[16:19], v[134:137], v[92:95], v[16:19]
	v_mfma_f32_16x16x32_bf16 v[0:3], v[172:175], v[92:95], v[0:3]
	s_add_u32 m0, s44, 0xa000
	s_nop 0
	global_load_lds_dwordx4 v70, s[100:101]
	ds_read_b128 v[134:137], v122 offset:53248
	s_waitcnt lgkmcnt(2)
	v_mfma_f32_16x16x32_bf16 v[60:63], v[204:207], v[180:183], v[60:63]
	s_waitcnt lgkmcnt(1)
	v_mfma_f32_16x16x32_bf16 v[40:43], v[208:211], v[180:183], v[40:43]
	s_add_u32 m0, s44, 0xb000
	s_nop 0
	global_load_lds_dwordx4 v71, s[100:101]
	s_add_u32 s98, s98, 0x80
	s_addc_u32 s99, s99, 0
	s_add_u32 s100, s100, 0x80
	s_addc_u32 s101, s101, 0
	ds_read_b128 v[172:175], v122 offset:55296
	s_waitcnt lgkmcnt(1)
	v_mfma_f32_16x16x32_bf16 v[28:31], v[134:137], v[180:183], v[28:31]
	s_waitcnt lgkmcnt(0)
	v_mfma_f32_16x16x32_bf16 v[12:15], v[172:175], v[180:183], v[12:15]
	v_mfma_f32_16x16x32_bf16 v[56:59], v[204:207], v[188:191], v[56:59]
	v_mfma_f32_16x16x32_bf16 v[44:47], v[208:211], v[188:191], v[44:47]
	v_mfma_f32_16x16x32_bf16 v[24:27], v[134:137], v[188:191], v[24:27]
	v_mfma_f32_16x16x32_bf16 v[8:11], v[172:175], v[188:191], v[8:11]
	v_mfma_f32_16x16x32_bf16 v[52:55], v[204:207], v[192:195], v[52:55]
	v_mfma_f32_16x16x32_bf16 v[36:39], v[208:211], v[192:195], v[36:39]
	v_mfma_f32_16x16x32_bf16 v[20:23], v[134:137], v[192:195], v[20:23]
	v_mfma_f32_16x16x32_bf16 v[4:7], v[172:175], v[192:195], v[4:7]
	v_mfma_f32_16x16x32_bf16 v[48:51], v[204:207], v[200:203], v[48:51]
	v_mfma_f32_16x16x32_bf16 v[32:35], v[208:211], v[200:203], v[32:35]
	v_mfma_f32_16x16x32_bf16 v[16:19], v[134:137], v[200:203], v[16:19]
	v_mfma_f32_16x16x32_bf16 v[0:3], v[172:175], v[200:203], v[0:3]
	s_setprio 0
	s_mov_b32 s43, s42
	s_waitcnt vmcnt(0) lgkmcnt(0)
	s_barrier
	s_cmp_lt_u32 s43, 16
	s_cbranch_scc1 .LBB0_463
	s_waitcnt vmcnt(0)
	s_and_b32 s2, s49, 7
	s_and_b32 s26, s69, 7
	s_lshl_b32 s26, s26, 3
	s_or_b32 s2, s2, s26
	s_lshl_b32 s2, s2, 7
	s_lshr_b32 s26, s49, 3
	s_lshl_b32 s26, s26, 7
	v_readlane_b32 s42, v253, 0
	v_readlane_b32 s43, v253, 1
	s_load_dwordx2 s[98:99], s[42:43], 0x160
	s_load_dwordx2 s[100:101], s[42:43], 0x88
	s_cmp_lt_u32 s2, 0x1000
	s_cselect_b32 s44, 0, 8
	s_load_dwordx2 s[42:43], s[42:43], s44
	v_and_b32_e32 v227, 15, v146
	v_bfe_u32 v228, v146, 7, 1
	v_lshl_add_u32 v227, v228, 6, v227
	v_add_u32_e32 v227, s2, v227
	v_bfe_u32 v228, v146, 4, 2
	v_lshlrev_b32_e32 v228, 2, v228
	v_bfe_u32 v218, v146, 6, 1
	v_lshl_add_u32 v228, v218, 6, v228
	v_add_u32_e32 v228, s26, v228
	v_lshlrev_b32_e32 v218, 2, v228
	v_lshl_add_u32 v96, v227, 12, v218
	v_add_u32_e32 v114, 0x10000, v96
	v_add_u32_e32 v115, 0x20000, v96
	v_add_u32_e32 v142, 0x30000, v96
	v_lshrrev_b32_e32 v214, 1, v96
	v_add_u32_e32 v214, 0xdc40000, v214
	v_lshrrev_b32_e32 v215, 1, v114
	v_add_u32_e32 v215, 0xdc40000, v215
	v_lshrrev_b32_e32 v216, 1, v115
	v_add_u32_e32 v216, 0xdc40000, v216
	v_lshrrev_b32_e32 v217, 1, v142
	v_add_u32_e32 v217, 0xdc40000, v217
	v_lshlrev_b32_e32 v222, 2, v227
	v_add_u32_e32 v222, 0xfa8a100, v222
	s_sub_u32 s44, s2, 0x1000
	s_lshr_b32 s44, s44, 10
	s_add_u32 s44, s44, 1
	s_cmp_lt_u32 s2, 0x1000
	s_cselect_b32 s44, 0, s44
	s_mul_i32 s44, s44, 0x3000
	v_add_u32_e32 v219, s44, v218
	v_add_u32_e32 v221, 0xf450000, v219
	v_add_u32_e32 v219, 0xf442000, v219
	v_mbcnt_lo_u32_b32 v229, -1, 0
	v_mbcnt_hi_u32_b32 v229, -1, v229
	v_xor_b32_e32 v244, 32, v229
	v_xor_b32_e32 v229, 16, v229
	v_lshlrev_b32_e32 v244, 2, v244
	v_lshlrev_b32_e32 v229, 2, v229
	s_waitcnt lgkmcnt(0)
	s_cmp_lt_u32 s2, 0x1000
	s_cselect_b32 s44, 0, 0x1000000
	s_sub_u32 s42, s42, s44
	s_subb_u32 s43, s43, 0
	global_load_dwordx4 v[164:167], v219, s[98:99]
	global_load_dwordx4 v[168:171], v219, s[98:99] offset:64
	global_load_dwordx4 v[172:175], v219, s[98:99] offset:128
	global_load_dwordx4 v[176:179], v219, s[98:99] offset:192
	global_load_dwordx4 v[180:183], v218, s[100:101]
	global_load_dwordx4 v[184:187], v218, s[100:101] offset:64
	global_load_dwordx4 v[188:191], v218, s[100:101] offset:128
	global_load_dwordx4 v[192:195], v218, s[100:101] offset:192
	global_load_dwordx4 v[196:199], v221, s[98:99]
	global_load_dwordx4 v[200:203], v221, s[98:99] offset:64
	global_load_dwordx4 v[204:207], v221, s[98:99] offset:128
	global_load_dwordx4 v[208:211], v221, s[98:99] offset:192
	global_load_dwordx4 v[64:67], v96, s[42:43] nt
	global_load_dwordx4 v[80:83], v114, s[42:43] nt
	global_load_dwordx4 v[98:101], v115, s[42:43] nt
	global_load_dwordx4 v[126:129], v142, s[42:43] nt
	global_load_dwordx4 v[68:71], v96, s[42:43] offset:64 nt
	global_load_dwordx4 v[84:87], v114, s[42:43] offset:64 nt
	global_load_dwordx4 v[102:105], v115, s[42:43] offset:64 nt
	global_load_dwordx4 v[130:133], v142, s[42:43] offset:64 nt
	global_load_dwordx4 v[72:75], v96, s[42:43] offset:128 nt
	global_load_dwordx4 v[88:91], v114, s[42:43] offset:128 nt
	global_load_dwordx4 v[106:109], v115, s[42:43] offset:128 nt
	global_load_dwordx4 v[134:137], v142, s[42:43] offset:128 nt
	global_load_dwordx4 v[76:79], v96, s[42:43] offset:192 nt
	global_load_dwordx4 v[92:95], v114, s[42:43] offset:192 nt
	global_load_dwordx4 v[110:113], v115, s[42:43] offset:192 nt
	global_load_dwordx4 v[138:141], v142, s[42:43] offset:192 nt
	v_mov_b32_e32 v223, 0
	v_mov_b32_e32 v224, 0
	v_mov_b32_e32 v225, 0
	v_mov_b32_e32 v226, 0
	s_waitcnt vmcnt(16)
	v_pk_add_f32 v[196:197], v[196:197], 1.0 op_sel_hi:[1,0]
	v_pk_add_f32 v[198:199], v[198:199], 1.0 op_sel_hi:[1,0]
	v_pk_mul_f32 v[196:197], v[180:181], v[196:197]
	v_pk_mul_f32 v[198:199], v[182:183], v[198:199]
	v_pk_add_f32 v[200:201], v[200:201], 1.0 op_sel_hi:[1,0]
	v_pk_add_f32 v[202:203], v[202:203], 1.0 op_sel_hi:[1,0]
	v_pk_mul_f32 v[200:201], v[184:185], v[200:201]
	v_pk_mul_f32 v[202:203], v[186:187], v[202:203]
	v_pk_add_f32 v[204:205], v[204:205], 1.0 op_sel_hi:[1,0]
	v_pk_add_f32 v[206:207], v[206:207], 1.0 op_sel_hi:[1,0]
	v_pk_mul_f32 v[204:205], v[188:189], v[204:205]
	v_pk_mul_f32 v[206:207], v[190:191], v[206:207]
	v_pk_add_f32 v[208:209], v[208:209], 1.0 op_sel_hi:[1,0]
	v_pk_add_f32 v[210:211], v[210:211], 1.0 op_sel_hi:[1,0]
	v_pk_mul_f32 v[208:209], v[192:193], v[208:209]
	v_pk_mul_f32 v[210:211], v[194:195], v[210:211]
	s_waitcnt vmcnt(15)
	v_pk_fma_f32 v[60:61], v[60:61], v[164:165], v[64:65]
	v_pk_fma_f32 v[62:63], v[62:63], v[166:167], v[66:67]
	global_store_dwordx4 v96, v[60:63], s[98:99]
	v_pk_mul_f32 v[64:65], v[196:197], v[60:61]
	v_pk_mul_f32 v[66:67], v[198:199], v[62:63]
	v_cvt_pk_bf16_f32 v64, v64, v65
	v_cvt_pk_bf16_f32 v65, v66, v67
	global_store_dwordx2 v214, v[64:65], s[98:99]
	v_pk_mul_f32 v[66:67], v[60:61], v[60:61]
	v_pk_fma_f32 v[66:67], v[62:63], v[62:63], v[66:67]
	v_add_f32_e32 v227, v66, v67
	v_add_f32_e32 v223, v223, v227
	s_waitcnt vmcnt(16)
	v_pk_fma_f32 v[56:57], v[56:57], v[164:165], v[80:81]
	v_pk_fma_f32 v[58:59], v[58:59], v[166:167], v[82:83]
	global_store_dwordx4 v114, v[56:59], s[98:99]
	v_pk_mul_f32 v[80:81], v[196:197], v[56:57]
	v_pk_mul_f32 v[82:83], v[198:199], v[58:59]
	v_cvt_pk_bf16_f32 v80, v80, v81
	v_cvt_pk_bf16_f32 v81, v82, v83
	global_store_dwordx2 v215, v[80:81], s[98:99]
	v_pk_mul_f32 v[82:83], v[56:57], v[56:57]
	v_pk_fma_f32 v[82:83], v[58:59], v[58:59], v[82:83]
	v_add_f32_e32 v227, v82, v83
	v_add_f32_e32 v224, v224, v227
	s_waitcnt vmcnt(17)
	v_pk_fma_f32 v[52:53], v[52:53], v[164:165], v[98:99]
	v_pk_fma_f32 v[54:55], v[54:55], v[166:167], v[100:101]
	global_store_dwordx4 v115, v[52:55], s[98:99]
	v_pk_mul_f32 v[98:99], v[196:197], v[52:53]
	v_pk_mul_f32 v[100:101], v[198:199], v[54:55]
	v_cvt_pk_bf16_f32 v98, v98, v99
	v_cvt_pk_bf16_f32 v99, v100, v101
	global_store_dwordx2 v216, v[98:99], s[98:99]
	v_pk_mul_f32 v[100:101], v[52:53], v[52:53]
	v_pk_fma_f32 v[100:101], v[54:55], v[54:55], v[100:101]
	v_add_f32_e32 v227, v100, v101
	v_add_f32_e32 v225, v225, v227
	s_waitcnt vmcnt(18)
	v_pk_fma_f32 v[48:49], v[48:49], v[164:165], v[126:127]
	v_pk_fma_f32 v[50:51], v[50:51], v[166:167], v[128:129]
	global_store_dwordx4 v142, v[48:51], s[98:99]
	v_pk_mul_f32 v[126:127], v[196:197], v[48:49]
	v_pk_mul_f32 v[128:129], v[198:199], v[50:51]
	v_cvt_pk_bf16_f32 v126, v126, v127
	v_cvt_pk_bf16_f32 v127, v128, v129
	global_store_dwordx2 v217, v[126:127], s[98:99]
	v_pk_mul_f32 v[128:129], v[48:49], v[48:49]
	v_pk_fma_f32 v[128:129], v[50:51], v[50:51], v[128:129]
	v_add_f32_e32 v227, v128, v129
	v_add_f32_e32 v226, v226, v227
	s_waitcnt vmcnt(19)
	v_pk_fma_f32 v[40:41], v[40:41], v[168:169], v[68:69]
	v_pk_fma_f32 v[42:43], v[42:43], v[170:171], v[70:71]
	global_store_dwordx4 v96, v[40:43], s[98:99] offset:64
	v_pk_mul_f32 v[68:69], v[200:201], v[40:41]
	v_pk_mul_f32 v[70:71], v[202:203], v[42:43]
	v_cvt_pk_bf16_f32 v68, v68, v69
	v_cvt_pk_bf16_f32 v69, v70, v71
	global_store_dwordx2 v214, v[68:69], s[98:99] offset:32
	v_pk_mul_f32 v[70:71], v[40:41], v[40:41]
	v_pk_fma_f32 v[70:71], v[42:43], v[42:43], v[70:71]
	v_add_f32_e32 v227, v70, v71
	v_add_f32_e32 v223, v223, v227
	s_waitcnt vmcnt(20)
	v_pk_fma_f32 v[44:45], v[44:45], v[168:169], v[84:85]
	v_pk_fma_f32 v[46:47], v[46:47], v[170:171], v[86:87]
	global_store_dwordx4 v114, v[44:47], s[98:99] offset:64
	v_pk_mul_f32 v[84:85], v[200:201], v[44:45]
	v_pk_mul_f32 v[86:87], v[202:203], v[46:47]
	v_cvt_pk_bf16_f32 v84, v84, v85
	v_cvt_pk_bf16_f32 v85, v86, v87
	global_store_dwordx2 v215, v[84:85], s[98:99] offset:32
	v_pk_mul_f32 v[86:87], v[44:45], v[44:45]
	v_pk_fma_f32 v[86:87], v[46:47], v[46:47], v[86:87]
	v_add_f32_e32 v227, v86, v87
	v_add_f32_e32 v224, v224, v227
	s_waitcnt vmcnt(21)
	v_pk_fma_f32 v[36:37], v[36:37], v[168:169], v[102:103]
	v_pk_fma_f32 v[38:39], v[38:39], v[170:171], v[104:105]
	global_store_dwordx4 v115, v[36:39], s[98:99] offset:64
	v_pk_mul_f32 v[102:103], v[200:201], v[36:37]
	v_pk_mul_f32 v[104:105], v[202:203], v[38:39]
	v_cvt_pk_bf16_f32 v102, v102, v103
	v_cvt_pk_bf16_f32 v103, v104, v105
	global_store_dwordx2 v216, v[102:103], s[98:99] offset:32
	v_pk_mul_f32 v[104:105], v[36:37], v[36:37]
	v_pk_fma_f32 v[104:105], v[38:39], v[38:39], v[104:105]
	v_add_f32_e32 v227, v104, v105
	v_add_f32_e32 v225, v225, v227
	s_waitcnt vmcnt(22)
	v_pk_fma_f32 v[32:33], v[32:33], v[168:169], v[130:131]
	v_pk_fma_f32 v[34:35], v[34:35], v[170:171], v[132:133]
	global_store_dwordx4 v142, v[32:35], s[98:99] offset:64
	v_pk_mul_f32 v[130:131], v[200:201], v[32:33]
	v_pk_mul_f32 v[132:133], v[202:203], v[34:35]
	v_cvt_pk_bf16_f32 v130, v130, v131
	v_cvt_pk_bf16_f32 v131, v132, v133
	global_store_dwordx2 v217, v[130:131], s[98:99] offset:32
	v_pk_mul_f32 v[132:133], v[32:33], v[32:33]
	v_pk_fma_f32 v[132:133], v[34:35], v[34:35], v[132:133]
	v_add_f32_e32 v227, v132, v133
	v_add_f32_e32 v226, v226, v227
	s_waitcnt vmcnt(23)
	v_pk_fma_f32 v[28:29], v[28:29], v[172:173], v[72:73]
	v_pk_fma_f32 v[30:31], v[30:31], v[174:175], v[74:75]
	global_store_dwordx4 v96, v[28:31], s[98:99] offset:128
	v_pk_mul_f32 v[72:73], v[204:205], v[28:29]
	v_pk_mul_f32 v[74:75], v[206:207], v[30:31]
	v_cvt_pk_bf16_f32 v72, v72, v73
	v_cvt_pk_bf16_f32 v73, v74, v75
	global_store_dwordx2 v214, v[72:73], s[98:99] offset:64
	v_pk_mul_f32 v[74:75], v[28:29], v[28:29]
	v_pk_fma_f32 v[74:75], v[30:31], v[30:31], v[74:75]
	v_add_f32_e32 v227, v74, v75
	v_add_f32_e32 v223, v223, v227
	s_waitcnt vmcnt(24)
	v_pk_fma_f32 v[24:25], v[24:25], v[172:173], v[88:89]
	v_pk_fma_f32 v[26:27], v[26:27], v[174:175], v[90:91]
	global_store_dwordx4 v114, v[24:27], s[98:99] offset:128
	v_pk_mul_f32 v[88:89], v[204:205], v[24:25]
	v_pk_mul_f32 v[90:91], v[206:207], v[26:27]
	v_cvt_pk_bf16_f32 v88, v88, v89
	v_cvt_pk_bf16_f32 v89, v90, v91
	global_store_dwordx2 v215, v[88:89], s[98:99] offset:64
	v_pk_mul_f32 v[90:91], v[24:25], v[24:25]
	v_pk_fma_f32 v[90:91], v[26:27], v[26:27], v[90:91]
	v_add_f32_e32 v227, v90, v91
	v_add_f32_e32 v224, v224, v227
	s_waitcnt vmcnt(25)
	v_pk_fma_f32 v[20:21], v[20:21], v[172:173], v[106:107]
	v_pk_fma_f32 v[22:23], v[22:23], v[174:175], v[108:109]
	global_store_dwordx4 v115, v[20:23], s[98:99] offset:128
	v_pk_mul_f32 v[106:107], v[204:205], v[20:21]
	v_pk_mul_f32 v[108:109], v[206:207], v[22:23]
	v_cvt_pk_bf16_f32 v106, v106, v107
	v_cvt_pk_bf16_f32 v107, v108, v109
	global_store_dwordx2 v216, v[106:107], s[98:99] offset:64
	v_pk_mul_f32 v[108:109], v[20:21], v[20:21]
	v_pk_fma_f32 v[108:109], v[22:23], v[22:23], v[108:109]
	v_add_f32_e32 v227, v108, v109
	v_add_f32_e32 v225, v225, v227
	s_waitcnt vmcnt(26)
	v_pk_fma_f32 v[16:17], v[16:17], v[172:173], v[134:135]
	v_pk_fma_f32 v[18:19], v[18:19], v[174:175], v[136:137]
	global_store_dwordx4 v142, v[16:19], s[98:99] offset:128
	v_pk_mul_f32 v[134:135], v[204:205], v[16:17]
	v_pk_mul_f32 v[136:137], v[206:207], v[18:19]
	v_cvt_pk_bf16_f32 v134, v134, v135
	v_cvt_pk_bf16_f32 v135, v136, v137
	global_store_dwordx2 v217, v[134:135], s[98:99] offset:64
	v_pk_mul_f32 v[136:137], v[16:17], v[16:17]
	v_pk_fma_f32 v[136:137], v[18:19], v[18:19], v[136:137]
	v_add_f32_e32 v227, v136, v137
	v_add_f32_e32 v226, v226, v227
	s_waitcnt vmcnt(27)
	v_pk_fma_f32 v[12:13], v[12:13], v[176:177], v[76:77]
	v_pk_fma_f32 v[14:15], v[14:15], v[178:179], v[78:79]
	global_store_dwordx4 v96, v[12:15], s[98:99] offset:192
	v_pk_mul_f32 v[76:77], v[208:209], v[12:13]
	v_pk_mul_f32 v[78:79], v[210:211], v[14:15]
	v_cvt_pk_bf16_f32 v76, v76, v77
	v_cvt_pk_bf16_f32 v77, v78, v79
	global_store_dwordx2 v214, v[76:77], s[98:99] offset:96
	v_pk_mul_f32 v[78:79], v[12:13], v[12:13]
	v_pk_fma_f32 v[78:79], v[14:15], v[14:15], v[78:79]
	v_add_f32_e32 v227, v78, v79
	v_add_f32_e32 v223, v223, v227
	s_waitcnt vmcnt(28)
	v_pk_fma_f32 v[8:9], v[8:9], v[176:177], v[92:93]
	v_pk_fma_f32 v[10:11], v[10:11], v[178:179], v[94:95]
	global_store_dwordx4 v114, v[8:11], s[98:99] offset:192
	v_pk_mul_f32 v[92:93], v[208:209], v[8:9]
	v_pk_mul_f32 v[94:95], v[210:211], v[10:11]
	v_cvt_pk_bf16_f32 v92, v92, v93
	v_cvt_pk_bf16_f32 v93, v94, v95
	global_store_dwordx2 v215, v[92:93], s[98:99] offset:96
	v_pk_mul_f32 v[94:95], v[8:9], v[8:9]
	v_pk_fma_f32 v[94:95], v[10:11], v[10:11], v[94:95]
	v_add_f32_e32 v227, v94, v95
	v_add_f32_e32 v224, v224, v227
	s_waitcnt vmcnt(29)
	v_pk_fma_f32 v[4:5], v[4:5], v[176:177], v[110:111]
	v_pk_fma_f32 v[6:7], v[6:7], v[178:179], v[112:113]
	global_store_dwordx4 v115, v[4:7], s[98:99] offset:192
	v_pk_mul_f32 v[110:111], v[208:209], v[4:5]
	v_pk_mul_f32 v[112:113], v[210:211], v[6:7]
	v_cvt_pk_bf16_f32 v110, v110, v111
	v_cvt_pk_bf16_f32 v111, v112, v113
	global_store_dwordx2 v216, v[110:111], s[98:99] offset:96
	v_pk_mul_f32 v[112:113], v[4:5], v[4:5]
	v_pk_fma_f32 v[112:113], v[6:7], v[6:7], v[112:113]
	v_add_f32_e32 v227, v112, v113
	v_add_f32_e32 v225, v225, v227
	s_waitcnt vmcnt(30)
	v_pk_fma_f32 v[0:1], v[0:1], v[176:177], v[138:139]
	v_pk_fma_f32 v[2:3], v[2:3], v[178:179], v[140:141]
	global_store_dwordx4 v142, v[0:3], s[98:99] offset:192
	v_pk_mul_f32 v[138:139], v[208:209], v[0:1]
	v_pk_mul_f32 v[140:141], v[210:211], v[2:3]
	v_cvt_pk_bf16_f32 v138, v138, v139
	v_cvt_pk_bf16_f32 v139, v140, v141
	global_store_dwordx2 v217, v[138:139], s[98:99] offset:96
	v_pk_mul_f32 v[140:141], v[0:1], v[0:1]
	v_pk_fma_f32 v[140:141], v[2:3], v[2:3], v[140:141]
	v_add_f32_e32 v227, v140, v141
	v_add_f32_e32 v226, v226, v227
	ds_bpermute_b32 v64, v229, v223
	ds_bpermute_b32 v80, v229, v224
	ds_bpermute_b32 v98, v229, v225
	ds_bpermute_b32 v126, v229, v226
	s_waitcnt lgkmcnt(0)
	v_add_f32_e32 v223, v223, v64
	v_add_f32_e32 v224, v224, v80
	v_add_f32_e32 v225, v225, v98
	v_add_f32_e32 v226, v226, v126
	ds_bpermute_b32 v64, v244, v223
	ds_bpermute_b32 v80, v244, v224
	ds_bpermute_b32 v98, v244, v225
	ds_bpermute_b32 v126, v244, v226
	s_waitcnt lgkmcnt(0)
	v_add_f32_e32 v223, v223, v64
	v_add_f32_e32 v224, v224, v80
	v_add_f32_e32 v225, v225, v98
	v_add_f32_e32 v226, v226, v126
	s_mov_b64 exec, 0xffff
	global_atomic_add_f32 v222, v223, s[98:99]
	global_atomic_add_f32 v222, v224, s[98:99] offset:64
	global_atomic_add_f32 v222, v225, s[98:99] offset:128
	global_atomic_add_f32 v222, v226, s[98:99] offset:192
	s_mov_b64 exec, -1
	s_mov_b32 s98, 0
	s_branch .LBB0_461

.LBB0_676:
	s_add_i32 s33, s42, 2
	s_setprio 1
	ds_read_b128 v[126:129], v119 offset:32768
	ds_read_b128 v[134:137], v119 offset:34816
	ds_read_b128 v[130:133], v118
	ds_read_b128 v[138:141], v118 offset:2048
	ds_read_b128 v[162:165], v118 offset:4096
	ds_read_b128 v[166:169], v118 offset:6144
	s_waitcnt lgkmcnt(3)
	v_mfma_f32_16x16x32_bf16 v[64:67], v[126:129], v[130:133], v[64:67]
	ds_read_b128 v[170:173], v119 offset:36864
	v_mfma_f32_16x16x32_bf16 v[40:43], v[134:137], v[130:133], v[40:43]
	ds_read_b128 v[174:177], v119 offset:38912
	s_waitcnt lgkmcnt(1)
	v_mfma_f32_16x16x32_bf16 v[28:31], v[170:173], v[130:133], v[28:31]
	s_waitcnt lgkmcnt(0)
	v_mfma_f32_16x16x32_bf16 v[12:15], v[174:177], v[130:133], v[12:15]
	s_add_u32 m0, s44, 0x4000
	s_nop 0
	global_load_lds_dwordx4 v68, s[98:99]
	ds_read_b128 v[178:181], v120
	v_mfma_f32_16x16x32_bf16 v[60:63], v[126:129], v[138:141], v[60:63]
	v_mfma_f32_16x16x32_bf16 v[44:47], v[134:137], v[138:141], v[44:47]
	s_add_u32 m0, s44, 0x5000
	s_nop 0
	global_load_lds_dwordx4 v69, s[98:99]
	ds_read_b128 v[186:189], v120 offset:2048
	v_mfma_f32_16x16x32_bf16 v[24:27], v[170:173], v[138:141], v[24:27]
	v_mfma_f32_16x16x32_bf16 v[8:11], v[174:177], v[138:141], v[8:11]
	s_add_u32 m0, s44, 0x6000
	s_nop 0
	global_load_lds_dwordx4 v70, s[98:99]
	ds_read_b128 v[190:193], v120 offset:4096
	v_mfma_f32_16x16x32_bf16 v[52:55], v[126:129], v[162:165], v[52:55]
	v_mfma_f32_16x16x32_bf16 v[36:39], v[134:137], v[162:165], v[36:39]
	s_add_u32 m0, s44, 0x7000
	s_nop 0
	global_load_lds_dwordx4 v71, s[98:99]
	ds_read_b128 v[198:201], v120 offset:6144
	v_mfma_f32_16x16x32_bf16 v[20:23], v[170:173], v[162:165], v[20:23]
	v_mfma_f32_16x16x32_bf16 v[4:7], v[174:177], v[162:165], v[4:7]
	s_add_u32 m0, s44, 0xc000
	s_nop 0
	global_load_lds_dwordx4 v68, s[100:101]
	ds_read_b128 v[202:205], v121 offset:32768
	v_mfma_f32_16x16x32_bf16 v[48:51], v[126:129], v[166:169], v[48:51]
	v_mfma_f32_16x16x32_bf16 v[32:35], v[134:137], v[166:169], v[32:35]
	s_add_u32 m0, s44, 0xd000
	s_nop 0
	global_load_lds_dwordx4 v69, s[100:101]
	ds_read_b128 v[134:137], v121 offset:34816
	v_mfma_f32_16x16x32_bf16 v[16:19], v[170:173], v[166:169], v[16:19]
	v_mfma_f32_16x16x32_bf16 v[0:3], v[174:177], v[166:169], v[0:3]
	s_add_u32 m0, s44, 0xe000
	s_nop 0
	global_load_lds_dwordx4 v70, s[100:101]
	ds_read_b128 v[170:173], v121 offset:36864
	s_waitcnt lgkmcnt(2)
	v_mfma_f32_16x16x32_bf16 v[64:67], v[202:205], v[178:181], v[64:67]
	s_waitcnt lgkmcnt(1)
	v_mfma_f32_16x16x32_bf16 v[40:43], v[134:137], v[178:181], v[40:43]
	s_add_u32 m0, s44, 0xf000
	s_nop 0
	global_load_lds_dwordx4 v71, s[100:101]
	s_add_u32 s98, s98, 0x80
	s_addc_u32 s99, s99, 0
	s_add_u32 s100, s100, 0x80
	s_addc_u32 s101, s101, 0
	ds_read_b128 v[206:209], v121 offset:38912
	s_waitcnt lgkmcnt(1)
	v_mfma_f32_16x16x32_bf16 v[28:31], v[170:173], v[178:181], v[28:31]
	s_waitcnt lgkmcnt(0)
	v_mfma_f32_16x16x32_bf16 v[12:15], v[206:209], v[178:181], v[12:15]
	v_mfma_f32_16x16x32_bf16 v[60:63], v[202:205], v[186:189], v[60:63]
	v_mfma_f32_16x16x32_bf16 v[44:47], v[134:137], v[186:189], v[44:47]
	v_mfma_f32_16x16x32_bf16 v[24:27], v[170:173], v[186:189], v[24:27]
	v_mfma_f32_16x16x32_bf16 v[8:11], v[206:209], v[186:189], v[8:11]
	v_mfma_f32_16x16x32_bf16 v[52:55], v[202:205], v[190:193], v[52:55]
	v_mfma_f32_16x16x32_bf16 v[36:39], v[134:137], v[190:193], v[36:39]
	v_mfma_f32_16x16x32_bf16 v[20:23], v[170:173], v[190:193], v[20:23]
	v_mfma_f32_16x16x32_bf16 v[4:7], v[206:209], v[190:193], v[4:7]
	v_mfma_f32_16x16x32_bf16 v[48:51], v[202:205], v[198:201], v[48:51]
	v_mfma_f32_16x16x32_bf16 v[32:35], v[134:137], v[198:201], v[32:35]
	v_mfma_f32_16x16x32_bf16 v[16:19], v[170:173], v[198:201], v[16:19]
	v_mfma_f32_16x16x32_bf16 v[0:3], v[206:209], v[198:201], v[0:3]
	s_setprio 0
	s_waitcnt vmcnt(0) lgkmcnt(0)
	s_barrier
	s_setprio 1
	ds_read_b128 v[84:87], v119 offset:49152
	ds_read_b128 v[88:91], v119 offset:51200
	ds_read_b128 v[56:59], v118 offset:16384
	ds_read_b128 v[72:75], v118 offset:18432
	ds_read_b128 v[76:79], v118 offset:20480
	ds_read_b128 v[92:95], v118 offset:22528
	s_waitcnt lgkmcnt(3)
	v_mfma_f32_16x16x32_bf16 v[64:67], v[84:87], v[56:59], v[64:67]
	ds_read_b128 v[134:137], v119 offset:53248
	v_mfma_f32_16x16x32_bf16 v[40:43], v[88:91], v[56:59], v[40:43]
	ds_read_b128 v[170:173], v119 offset:55296
	s_waitcnt lgkmcnt(1)
	v_mfma_f32_16x16x32_bf16 v[28:31], v[134:137], v[56:59], v[28:31]
	s_waitcnt lgkmcnt(0)
	v_mfma_f32_16x16x32_bf16 v[12:15], v[170:173], v[56:59], v[12:15]
	s_add_u32 m0, s44, 0x0
	s_nop 0
	global_load_lds_dwordx4 v68, s[98:99]
	ds_read_b128 v[178:181], v120 offset:16384
	v_mfma_f32_16x16x32_bf16 v[60:63], v[84:87], v[72:75], v[60:63]
	v_mfma_f32_16x16x32_bf16 v[44:47], v[88:91], v[72:75], v[44:47]
	s_add_u32 m0, s44, 0x1000
	s_nop 0
	global_load_lds_dwordx4 v69, s[98:99]
	ds_read_b128 v[186:189], v120 offset:18432
	v_mfma_f32_16x16x32_bf16 v[24:27], v[134:137], v[72:75], v[24:27]
	v_mfma_f32_16x16x32_bf16 v[8:11], v[170:173], v[72:75], v[8:11]
	s_add_u32 m0, s44, 0x2000
	s_nop 0
	global_load_lds_dwordx4 v70, s[98:99]
	ds_read_b128 v[190:193], v120 offset:20480
	v_mfma_f32_16x16x32_bf16 v[52:55], v[84:87], v[76:79], v[52:55]
	v_mfma_f32_16x16x32_bf16 v[36:39], v[88:91], v[76:79], v[36:39]
	s_add_u32 m0, s44, 0x3000
	s_nop 0
	global_load_lds_dwordx4 v71, s[98:99]
	ds_read_b128 v[198:201], v120 offset:22528
	v_mfma_f32_16x16x32_bf16 v[20:23], v[134:137], v[76:79], v[20:23]
	v_mfma_f32_16x16x32_bf16 v[4:7], v[170:173], v[76:79], v[4:7]
	s_add_u32 m0, s44, 0x8000
	s_nop 0
	global_load_lds_dwordx4 v68, s[100:101]
	ds_read_b128 v[202:205], v121 offset:49152
	v_mfma_f32_16x16x32_bf16 v[48:51], v[84:87], v[92:95], v[48:51]
	v_mfma_f32_16x16x32_bf16 v[32:35], v[88:91], v[92:95], v[32:35]
	s_add_u32 m0, s44, 0x9000
	s_nop 0
	global_load_lds_dwordx4 v69, s[100:101]
	ds_read_b128 v[206:209], v121 offset:51200
	v_mfma_f32_16x16x32_bf16 v[16:19], v[134:137], v[92:95], v[16:19]
	v_mfma_f32_16x16x32_bf16 v[0:3], v[170:173], v[92:95], v[0:3]
	s_add_u32 m0, s44, 0xa000
	s_nop 0
	global_load_lds_dwordx4 v70, s[100:101]
	ds_read_b128 v[134:137], v121 offset:53248
	s_waitcnt lgkmcnt(2)
	v_mfma_f32_16x16x32_bf16 v[64:67], v[202:205], v[178:181], v[64:67]
	s_waitcnt lgkmcnt(1)
	v_mfma_f32_16x16x32_bf16 v[40:43], v[206:209], v[178:181], v[40:43]
	s_add_u32 m0, s44, 0xb000
	s_nop 0
	global_load_lds_dwordx4 v71, s[100:101]
	s_add_u32 s98, s98, 0x80
	s_addc_u32 s99, s99, 0
	s_add_u32 s100, s100, 0x80
	s_addc_u32 s101, s101, 0
	ds_read_b128 v[170:173], v121 offset:55296
	s_waitcnt lgkmcnt(1)
	v_mfma_f32_16x16x32_bf16 v[28:31], v[134:137], v[178:181], v[28:31]
	s_waitcnt lgkmcnt(0)
	v_mfma_f32_16x16x32_bf16 v[12:15], v[170:173], v[178:181], v[12:15]
	v_mfma_f32_16x16x32_bf16 v[60:63], v[202:205], v[186:189], v[60:63]
	v_mfma_f32_16x16x32_bf16 v[44:47], v[206:209], v[186:189], v[44:47]
	v_mfma_f32_16x16x32_bf16 v[24:27], v[134:137], v[186:189], v[24:27]
	v_mfma_f32_16x16x32_bf16 v[8:11], v[170:173], v[186:189], v[8:11]
	v_mfma_f32_16x16x32_bf16 v[52:55], v[202:205], v[190:193], v[52:55]
	v_mfma_f32_16x16x32_bf16 v[36:39], v[206:209], v[190:193], v[36:39]
	v_mfma_f32_16x16x32_bf16 v[20:23], v[134:137], v[190:193], v[20:23]
	v_mfma_f32_16x16x32_bf16 v[4:7], v[170:173], v[190:193], v[4:7]
	v_mfma_f32_16x16x32_bf16 v[48:51], v[202:205], v[198:201], v[48:51]
	v_mfma_f32_16x16x32_bf16 v[32:35], v[206:209], v[198:201], v[32:35]
	v_mfma_f32_16x16x32_bf16 v[16:19], v[134:137], v[198:201], v[16:19]
	v_mfma_f32_16x16x32_bf16 v[0:3], v[170:173], v[198:201], v[0:3]
	s_setprio 0
	s_mov_b32 s42, s33
	s_waitcnt vmcnt(0) lgkmcnt(0)
	s_barrier
	s_cmp_lt_u32 s42, 16
	s_cbranch_scc1 .LBB0_676
	s_waitcnt vmcnt(0)
	s_and_b32 s2, s9, 7
	s_and_b32 s28, s69, 7
	s_lshl_b32 s28, s28, 3
	s_or_b32 s2, s2, s28
	s_lshl_b32 s2, s2, 7
	s_lshr_b32 s28, s9, 3
	s_lshl_b32 s28, s28, 7
	v_readlane_b32 s44, v253, 0
	v_readlane_b32 s45, v253, 1
	s_load_dwordx2 s[98:99], s[44:45], 0x160
	s_load_dwordx2 s[100:101], s[44:45], 0xd8
	v_and_b32_e32 v227, 15, v146
	v_bfe_u32 v228, v146, 7, 1
	v_lshl_add_u32 v227, v228, 6, v227
	v_add_u32_e32 v227, s2, v227
	v_bfe_u32 v228, v146, 4, 2
	v_lshlrev_b32_e32 v228, 2, v228
	v_bfe_u32 v218, v146, 6, 1
	v_lshl_add_u32 v228, v218, 6, v228
	v_add_u32_e32 v228, s28, v228
	v_lshlrev_b32_e32 v218, 2, v228
	v_lshl_add_u32 v96, v227, 12, v218
	v_add_u32_e32 v114, 0x10000, v96
	v_add_u32_e32 v115, 0x20000, v96
	v_add_u32_e32 v142, 0x30000, v96
	v_lshrrev_b32_e32 v214, 1, v96
	v_add_u32_e32 v214, 0xdc40000, v214
	v_lshrrev_b32_e32 v215, 1, v114
	v_add_u32_e32 v215, 0xdc40000, v215
	v_lshrrev_b32_e32 v216, 1, v115
	v_add_u32_e32 v216, 0xdc40000, v216
	v_lshrrev_b32_e32 v217, 1, v142
	v_add_u32_e32 v217, 0xdc40000, v217
	v_lshlrev_b32_e32 v222, 2, v227
	v_add_u32_e32 v222, 0xfa92100, v222
	s_sub_u32 s33, s2, 0x1000
	s_lshr_b32 s33, s33, 10
	s_add_u32 s33, s33, 1
	s_cmp_lt_u32 s2, 0x1000
	s_cselect_b32 s33, 0, s33
	s_mul_i32 s33, s33, 0x3000
	v_add_u32_e32 v219, s33, v218
	v_add_u32_e32 v221, 0xf45f000, v219
	v_add_u32_e32 v219, 0xf451000, v219
	v_mbcnt_lo_u32_b32 v229, -1, 0
	v_mbcnt_hi_u32_b32 v229, -1, v229
	v_xor_b32_e32 v244, 32, v229
	v_xor_b32_e32 v229, 16, v229
	v_lshlrev_b32_e32 v244, 2, v244
	v_lshlrev_b32_e32 v229, 2, v229
	s_waitcnt lgkmcnt(0)
	s_mov_b64 s[44:45], s[98:99]
	global_load_dwordx4 v[162:165], v219, s[98:99]
	global_load_dwordx4 v[166:169], v219, s[98:99] offset:64
	global_load_dwordx4 v[170:173], v219, s[98:99] offset:128
	global_load_dwordx4 v[174:177], v219, s[98:99] offset:192
	global_load_dwordx4 v[178:181], v218, s[100:101]
	global_load_dwordx4 v[182:185], v218, s[100:101] offset:64
	global_load_dwordx4 v[186:189], v218, s[100:101] offset:128
	global_load_dwordx4 v[190:193], v218, s[100:101] offset:192
	global_load_dwordx4 v[194:197], v221, s[98:99]
	global_load_dwordx4 v[198:201], v221, s[98:99] offset:64
	global_load_dwordx4 v[202:205], v221, s[98:99] offset:128
	global_load_dwordx4 v[206:209], v221, s[98:99] offset:192
	global_load_dwordx4 v[56:59], v96, s[44:45]
	global_load_dwordx4 v[80:83], v114, s[44:45]
	global_load_dwordx4 v[98:101], v115, s[44:45]
	global_load_dwordx4 v[126:129], v142, s[44:45]
	global_load_dwordx4 v[68:71], v96, s[44:45] offset:64
	global_load_dwordx4 v[84:87], v114, s[44:45] offset:64
	global_load_dwordx4 v[102:105], v115, s[44:45] offset:64
	global_load_dwordx4 v[130:133], v142, s[44:45] offset:64
	global_load_dwordx4 v[72:75], v96, s[44:45] offset:128
	global_load_dwordx4 v[88:91], v114, s[44:45] offset:128
	global_load_dwordx4 v[106:109], v115, s[44:45] offset:128
	global_load_dwordx4 v[134:137], v142, s[44:45] offset:128
	global_load_dwordx4 v[76:79], v96, s[44:45] offset:192
	global_load_dwordx4 v[92:95], v114, s[44:45] offset:192
	global_load_dwordx4 v[110:113], v115, s[44:45] offset:192
	global_load_dwordx4 v[138:141], v142, s[44:45] offset:192
	v_mov_b32_e32 v223, 0
	v_mov_b32_e32 v224, 0
	v_mov_b32_e32 v225, 0
	v_mov_b32_e32 v226, 0
	s_waitcnt vmcnt(16)
	v_pk_add_f32 v[194:195], v[194:195], 1.0 op_sel_hi:[1,0]
	v_pk_add_f32 v[196:197], v[196:197], 1.0 op_sel_hi:[1,0]
	v_pk_mul_f32 v[194:195], v[178:179], v[194:195]
	v_pk_mul_f32 v[196:197], v[180:181], v[196:197]
	v_pk_add_f32 v[198:199], v[198:199], 1.0 op_sel_hi:[1,0]
	v_pk_add_f32 v[200:201], v[200:201], 1.0 op_sel_hi:[1,0]
	v_pk_mul_f32 v[198:199], v[182:183], v[198:199]
	v_pk_mul_f32 v[200:201], v[184:185], v[200:201]
	v_pk_add_f32 v[202:203], v[202:203], 1.0 op_sel_hi:[1,0]
	v_pk_add_f32 v[204:205], v[204:205], 1.0 op_sel_hi:[1,0]
	v_pk_mul_f32 v[202:203], v[186:187], v[202:203]
	v_pk_mul_f32 v[204:205], v[188:189], v[204:205]
	v_pk_add_f32 v[206:207], v[206:207], 1.0 op_sel_hi:[1,0]
	v_pk_add_f32 v[208:209], v[208:209], 1.0 op_sel_hi:[1,0]
	v_pk_mul_f32 v[206:207], v[190:191], v[206:207]
	v_pk_mul_f32 v[208:209], v[192:193], v[208:209]
	s_waitcnt vmcnt(15)
	v_pk_fma_f32 v[64:65], v[64:65], v[162:163], v[56:57]
	v_pk_fma_f32 v[66:67], v[66:67], v[164:165], v[58:59]
	global_store_dwordx4 v96, v[64:67], s[98:99]
	v_pk_mul_f32 v[56:57], v[194:195], v[64:65]
	v_pk_mul_f32 v[58:59], v[196:197], v[66:67]
	v_cvt_pk_bf16_f32 v56, v56, v57
	v_cvt_pk_bf16_f32 v57, v58, v59
	global_store_dwordx2 v214, v[56:57], s[98:99]
	v_pk_mul_f32 v[58:59], v[64:65], v[64:65]
	v_pk_fma_f32 v[58:59], v[66:67], v[66:67], v[58:59]
	v_add_f32_e32 v227, v58, v59
	v_add_f32_e32 v223, v223, v227
	s_waitcnt vmcnt(16)
	v_pk_fma_f32 v[60:61], v[60:61], v[162:163], v[80:81]
	v_pk_fma_f32 v[62:63], v[62:63], v[164:165], v[82:83]
	global_store_dwordx4 v114, v[60:63], s[98:99]
	v_pk_mul_f32 v[80:81], v[194:195], v[60:61]
	v_pk_mul_f32 v[82:83], v[196:197], v[62:63]
	v_cvt_pk_bf16_f32 v80, v80, v81
	v_cvt_pk_bf16_f32 v81, v82, v83
	global_store_dwordx2 v215, v[80:81], s[98:99]
	v_pk_mul_f32 v[82:83], v[60:61], v[60:61]
	v_pk_fma_f32 v[82:83], v[62:63], v[62:63], v[82:83]
	v_add_f32_e32 v227, v82, v83
	v_add_f32_e32 v224, v224, v227
	s_waitcnt vmcnt(17)
	v_pk_fma_f32 v[52:53], v[52:53], v[162:163], v[98:99]
	v_pk_fma_f32 v[54:55], v[54:55], v[164:165], v[100:101]
	global_store_dwordx4 v115, v[52:55], s[98:99]
	v_pk_mul_f32 v[98:99], v[194:195], v[52:53]
	v_pk_mul_f32 v[100:101], v[196:197], v[54:55]
	v_cvt_pk_bf16_f32 v98, v98, v99
	v_cvt_pk_bf16_f32 v99, v100, v101
	global_store_dwordx2 v216, v[98:99], s[98:99]
	v_pk_mul_f32 v[100:101], v[52:53], v[52:53]
	v_pk_fma_f32 v[100:101], v[54:55], v[54:55], v[100:101]
	v_add_f32_e32 v227, v100, v101
	v_add_f32_e32 v225, v225, v227
	s_waitcnt vmcnt(18)
	v_pk_fma_f32 v[48:49], v[48:49], v[162:163], v[126:127]
	v_pk_fma_f32 v[50:51], v[50:51], v[164:165], v[128:129]
	global_store_dwordx4 v142, v[48:51], s[98:99]
	v_pk_mul_f32 v[126:127], v[194:195], v[48:49]
	v_pk_mul_f32 v[128:129], v[196:197], v[50:51]
	v_cvt_pk_bf16_f32 v126, v126, v127
	v_cvt_pk_bf16_f32 v127, v128, v129
	global_store_dwordx2 v217, v[126:127], s[98:99]
	v_pk_mul_f32 v[128:129], v[48:49], v[48:49]
	v_pk_fma_f32 v[128:129], v[50:51], v[50:51], v[128:129]
	v_add_f32_e32 v227, v128, v129
	v_add_f32_e32 v226, v226, v227
	s_waitcnt vmcnt(19)
	v_pk_fma_f32 v[40:41], v[40:41], v[166:167], v[68:69]
	v_pk_fma_f32 v[42:43], v[42:43], v[168:169], v[70:71]
	global_store_dwordx4 v96, v[40:43], s[98:99] offset:64
	v_pk_mul_f32 v[68:69], v[198:199], v[40:41]
	v_pk_mul_f32 v[70:71], v[200:201], v[42:43]
	v_cvt_pk_bf16_f32 v68, v68, v69
	v_cvt_pk_bf16_f32 v69, v70, v71
	global_store_dwordx2 v214, v[68:69], s[98:99] offset:32
	v_pk_mul_f32 v[70:71], v[40:41], v[40:41]
	v_pk_fma_f32 v[70:71], v[42:43], v[42:43], v[70:71]
	v_add_f32_e32 v227, v70, v71
	v_add_f32_e32 v223, v223, v227
	s_waitcnt vmcnt(20)
	v_pk_fma_f32 v[44:45], v[44:45], v[166:167], v[84:85]
	v_pk_fma_f32 v[46:47], v[46:47], v[168:169], v[86:87]
	global_store_dwordx4 v114, v[44:47], s[98:99] offset:64
	v_pk_mul_f32 v[84:85], v[198:199], v[44:45]
	v_pk_mul_f32 v[86:87], v[200:201], v[46:47]
	v_cvt_pk_bf16_f32 v84, v84, v85
	v_cvt_pk_bf16_f32 v85, v86, v87
	global_store_dwordx2 v215, v[84:85], s[98:99] offset:32
	v_pk_mul_f32 v[86:87], v[44:45], v[44:45]
	v_pk_fma_f32 v[86:87], v[46:47], v[46:47], v[86:87]
	v_add_f32_e32 v227, v86, v87
	v_add_f32_e32 v224, v224, v227
	s_waitcnt vmcnt(21)
	v_pk_fma_f32 v[36:37], v[36:37], v[166:167], v[102:103]
	v_pk_fma_f32 v[38:39], v[38:39], v[168:169], v[104:105]
	global_store_dwordx4 v115, v[36:39], s[98:99] offset:64
	v_pk_mul_f32 v[102:103], v[198:199], v[36:37]
	v_pk_mul_f32 v[104:105], v[200:201], v[38:39]
	v_cvt_pk_bf16_f32 v102, v102, v103
	v_cvt_pk_bf16_f32 v103, v104, v105
	global_store_dwordx2 v216, v[102:103], s[98:99] offset:32
	v_pk_mul_f32 v[104:105], v[36:37], v[36:37]
	v_pk_fma_f32 v[104:105], v[38:39], v[38:39], v[104:105]
	v_add_f32_e32 v227, v104, v105
	v_add_f32_e32 v225, v225, v227
	s_waitcnt vmcnt(22)
	v_pk_fma_f32 v[32:33], v[32:33], v[166:167], v[130:131]
	v_pk_fma_f32 v[34:35], v[34:35], v[168:169], v[132:133]
	global_store_dwordx4 v142, v[32:35], s[98:99] offset:64
	v_pk_mul_f32 v[130:131], v[198:199], v[32:33]
	v_pk_mul_f32 v[132:133], v[200:201], v[34:35]
	v_cvt_pk_bf16_f32 v130, v130, v131
	v_cvt_pk_bf16_f32 v131, v132, v133
	global_store_dwordx2 v217, v[130:131], s[98:99] offset:32
	v_pk_mul_f32 v[132:133], v[32:33], v[32:33]
	v_pk_fma_f32 v[132:133], v[34:35], v[34:35], v[132:133]
	v_add_f32_e32 v227, v132, v133
	v_add_f32_e32 v226, v226, v227
	s_waitcnt vmcnt(23)
	v_pk_fma_f32 v[28:29], v[28:29], v[170:171], v[72:73]
	v_pk_fma_f32 v[30:31], v[30:31], v[172:173], v[74:75]
	global_store_dwordx4 v96, v[28:31], s[98:99] offset:128
	v_pk_mul_f32 v[72:73], v[202:203], v[28:29]
	v_pk_mul_f32 v[74:75], v[204:205], v[30:31]
	v_cvt_pk_bf16_f32 v72, v72, v73
	v_cvt_pk_bf16_f32 v73, v74, v75
	global_store_dwordx2 v214, v[72:73], s[98:99] offset:64
	v_pk_mul_f32 v[74:75], v[28:29], v[28:29]
	v_pk_fma_f32 v[74:75], v[30:31], v[30:31], v[74:75]
	v_add_f32_e32 v227, v74, v75
	v_add_f32_e32 v223, v223, v227
	s_waitcnt vmcnt(24)
	v_pk_fma_f32 v[24:25], v[24:25], v[170:171], v[88:89]
	v_pk_fma_f32 v[26:27], v[26:27], v[172:173], v[90:91]
	global_store_dwordx4 v114, v[24:27], s[98:99] offset:128
	v_pk_mul_f32 v[88:89], v[202:203], v[24:25]
	v_pk_mul_f32 v[90:91], v[204:205], v[26:27]
	v_cvt_pk_bf16_f32 v88, v88, v89
	v_cvt_pk_bf16_f32 v89, v90, v91
	global_store_dwordx2 v215, v[88:89], s[98:99] offset:64
	v_pk_mul_f32 v[90:91], v[24:25], v[24:25]
	v_pk_fma_f32 v[90:91], v[26:27], v[26:27], v[90:91]
	v_add_f32_e32 v227, v90, v91
	v_add_f32_e32 v224, v224, v227
	s_waitcnt vmcnt(25)
	v_pk_fma_f32 v[20:21], v[20:21], v[170:171], v[106:107]
	v_pk_fma_f32 v[22:23], v[22:23], v[172:173], v[108:109]
	global_store_dwordx4 v115, v[20:23], s[98:99] offset:128
	v_pk_mul_f32 v[106:107], v[202:203], v[20:21]
	v_pk_mul_f32 v[108:109], v[204:205], v[22:23]
	v_cvt_pk_bf16_f32 v106, v106, v107
	v_cvt_pk_bf16_f32 v107, v108, v109
	global_store_dwordx2 v216, v[106:107], s[98:99] offset:64
	v_pk_mul_f32 v[108:109], v[20:21], v[20:21]
	v_pk_fma_f32 v[108:109], v[22:23], v[22:23], v[108:109]
	v_add_f32_e32 v227, v108, v109
	v_add_f32_e32 v225, v225, v227
	s_waitcnt vmcnt(26)
	v_pk_fma_f32 v[16:17], v[16:17], v[170:171], v[134:135]
	v_pk_fma_f32 v[18:19], v[18:19], v[172:173], v[136:137]
	global_store_dwordx4 v142, v[16:19], s[98:99] offset:128
	v_pk_mul_f32 v[134:135], v[202:203], v[16:17]
	v_pk_mul_f32 v[136:137], v[204:205], v[18:19]
	v_cvt_pk_bf16_f32 v134, v134, v135
	v_cvt_pk_bf16_f32 v135, v136, v137
	global_store_dwordx2 v217, v[134:135], s[98:99] offset:64
	v_pk_mul_f32 v[136:137], v[16:17], v[16:17]
	v_pk_fma_f32 v[136:137], v[18:19], v[18:19], v[136:137]
	v_add_f32_e32 v227, v136, v137
	v_add_f32_e32 v226, v226, v227
	s_waitcnt vmcnt(27)
	v_pk_fma_f32 v[12:13], v[12:13], v[174:175], v[76:77]
	v_pk_fma_f32 v[14:15], v[14:15], v[176:177], v[78:79]
	global_store_dwordx4 v96, v[12:15], s[98:99] offset:192
	v_pk_mul_f32 v[76:77], v[206:207], v[12:13]
	v_pk_mul_f32 v[78:79], v[208:209], v[14:15]
	v_cvt_pk_bf16_f32 v76, v76, v77
	v_cvt_pk_bf16_f32 v77, v78, v79
	global_store_dwordx2 v214, v[76:77], s[98:99] offset:96
	v_pk_mul_f32 v[78:79], v[12:13], v[12:13]
	v_pk_fma_f32 v[78:79], v[14:15], v[14:15], v[78:79]
	v_add_f32_e32 v227, v78, v79
	v_add_f32_e32 v223, v223, v227
	s_waitcnt vmcnt(28)
	v_pk_fma_f32 v[8:9], v[8:9], v[174:175], v[92:93]
	v_pk_fma_f32 v[10:11], v[10:11], v[176:177], v[94:95]
	global_store_dwordx4 v114, v[8:11], s[98:99] offset:192
	v_pk_mul_f32 v[92:93], v[206:207], v[8:9]
	v_pk_mul_f32 v[94:95], v[208:209], v[10:11]
	v_cvt_pk_bf16_f32 v92, v92, v93
	v_cvt_pk_bf16_f32 v93, v94, v95
	global_store_dwordx2 v215, v[92:93], s[98:99] offset:96
	v_pk_mul_f32 v[94:95], v[8:9], v[8:9]
	v_pk_fma_f32 v[94:95], v[10:11], v[10:11], v[94:95]
	v_add_f32_e32 v227, v94, v95
	v_add_f32_e32 v224, v224, v227
	s_waitcnt vmcnt(29)
	v_pk_fma_f32 v[4:5], v[4:5], v[174:175], v[110:111]
	v_pk_fma_f32 v[6:7], v[6:7], v[176:177], v[112:113]
	global_store_dwordx4 v115, v[4:7], s[98:99] offset:192
	v_pk_mul_f32 v[110:111], v[206:207], v[4:5]
	v_pk_mul_f32 v[112:113], v[208:209], v[6:7]
	v_cvt_pk_bf16_f32 v110, v110, v111
	v_cvt_pk_bf16_f32 v111, v112, v113
	global_store_dwordx2 v216, v[110:111], s[98:99] offset:96
	v_pk_mul_f32 v[112:113], v[4:5], v[4:5]
	v_pk_fma_f32 v[112:113], v[6:7], v[6:7], v[112:113]
	v_add_f32_e32 v227, v112, v113
	v_add_f32_e32 v225, v225, v227
	s_waitcnt vmcnt(30)
	v_pk_fma_f32 v[0:1], v[0:1], v[174:175], v[138:139]
	v_pk_fma_f32 v[2:3], v[2:3], v[176:177], v[140:141]
	global_store_dwordx4 v142, v[0:3], s[98:99] offset:192
	v_pk_mul_f32 v[138:139], v[206:207], v[0:1]
	v_pk_mul_f32 v[140:141], v[208:209], v[2:3]
	v_cvt_pk_bf16_f32 v138, v138, v139
	v_cvt_pk_bf16_f32 v139, v140, v141
	global_store_dwordx2 v217, v[138:139], s[98:99] offset:96
	v_pk_mul_f32 v[140:141], v[0:1], v[0:1]
	v_pk_fma_f32 v[140:141], v[2:3], v[2:3], v[140:141]
	v_add_f32_e32 v227, v140, v141
	v_add_f32_e32 v226, v226, v227
	ds_bpermute_b32 v56, v229, v223
	ds_bpermute_b32 v80, v229, v224
	ds_bpermute_b32 v98, v229, v225
	ds_bpermute_b32 v126, v229, v226
	s_waitcnt lgkmcnt(0)
	v_add_f32_e32 v223, v223, v56
	v_add_f32_e32 v224, v224, v80
	v_add_f32_e32 v225, v225, v98
	v_add_f32_e32 v226, v226, v126
	ds_bpermute_b32 v56, v244, v223
	ds_bpermute_b32 v80, v244, v224
	ds_bpermute_b32 v98, v244, v225
	ds_bpermute_b32 v126, v244, v226
	s_waitcnt lgkmcnt(0)
	v_add_f32_e32 v223, v223, v56
	v_add_f32_e32 v224, v224, v80
	v_add_f32_e32 v225, v225, v98
	v_add_f32_e32 v226, v226, v126
	s_mov_b64 exec, 0xffff
	global_atomic_add_f32 v222, v223, s[98:99]
	global_atomic_add_f32 v222, v224, s[98:99] offset:64
	global_atomic_add_f32 v222, v225, s[98:99] offset:128
	global_atomic_add_f32 v222, v226, s[98:99] offset:192
	s_mov_b64 exec, -1
	s_mov_b32 s98, 0
	s_branch .LBB0_674

.LBB0_1101:
	s_add_i32 s33, s40, 2
	s_setprio 1
	ds_read_b128 v[126:129], v119 offset:32768
	ds_read_b128 v[134:137], v119 offset:34816
	ds_read_b128 v[130:133], v118
	ds_read_b128 v[138:141], v118 offset:2048
	ds_read_b128 v[160:163], v118 offset:4096
	ds_read_b128 v[164:167], v118 offset:6144
	s_waitcnt lgkmcnt(3)
	v_mfma_f32_16x16x32_bf16 v[64:67], v[126:129], v[130:133], v[64:67]
	ds_read_b128 v[168:171], v119 offset:36864
	v_mfma_f32_16x16x32_bf16 v[40:43], v[134:137], v[130:133], v[40:43]
	ds_read_b128 v[172:175], v119 offset:38912
	s_waitcnt lgkmcnt(1)
	v_mfma_f32_16x16x32_bf16 v[28:31], v[168:171], v[130:133], v[28:31]
	s_waitcnt lgkmcnt(0)
	v_mfma_f32_16x16x32_bf16 v[12:15], v[172:175], v[130:133], v[12:15]
	s_add_u32 m0, s42, 0x4000
	s_nop 0
	global_load_lds_dwordx4 v68, s[98:99]
	ds_read_b128 v[176:179], v120
	v_mfma_f32_16x16x32_bf16 v[60:63], v[126:129], v[138:141], v[60:63]
	v_mfma_f32_16x16x32_bf16 v[44:47], v[134:137], v[138:141], v[44:47]
	s_add_u32 m0, s42, 0x5000
	s_nop 0
	global_load_lds_dwordx4 v69, s[98:99]
	ds_read_b128 v[184:187], v120 offset:2048
	v_mfma_f32_16x16x32_bf16 v[24:27], v[168:171], v[138:141], v[24:27]
	v_mfma_f32_16x16x32_bf16 v[8:11], v[172:175], v[138:141], v[8:11]
	s_add_u32 m0, s42, 0x6000
	s_nop 0
	global_load_lds_dwordx4 v70, s[98:99]
	ds_read_b128 v[188:191], v120 offset:4096
	v_mfma_f32_16x16x32_bf16 v[52:55], v[126:129], v[160:163], v[52:55]
	v_mfma_f32_16x16x32_bf16 v[36:39], v[134:137], v[160:163], v[36:39]
	s_add_u32 m0, s42, 0x7000
	s_nop 0
	global_load_lds_dwordx4 v71, s[98:99]
	ds_read_b128 v[196:199], v120 offset:6144
	v_mfma_f32_16x16x32_bf16 v[20:23], v[168:171], v[160:163], v[20:23]
	v_mfma_f32_16x16x32_bf16 v[4:7], v[172:175], v[160:163], v[4:7]
	s_add_u32 m0, s42, 0xc000
	s_nop 0
	global_load_lds_dwordx4 v68, s[100:101]
	ds_read_b128 v[200:203], v121 offset:32768
	v_mfma_f32_16x16x32_bf16 v[48:51], v[126:129], v[164:167], v[48:51]
	v_mfma_f32_16x16x32_bf16 v[32:35], v[134:137], v[164:167], v[32:35]
	s_add_u32 m0, s42, 0xd000
	s_nop 0
	global_load_lds_dwordx4 v69, s[100:101]
	ds_read_b128 v[134:137], v121 offset:34816
	v_mfma_f32_16x16x32_bf16 v[16:19], v[168:171], v[164:167], v[16:19]
	v_mfma_f32_16x16x32_bf16 v[0:3], v[172:175], v[164:167], v[0:3]
	s_add_u32 m0, s42, 0xe000
	s_nop 0
	global_load_lds_dwordx4 v70, s[100:101]
	ds_read_b128 v[168:171], v121 offset:36864
	s_waitcnt lgkmcnt(2)
	v_mfma_f32_16x16x32_bf16 v[64:67], v[200:203], v[176:179], v[64:67]
	s_waitcnt lgkmcnt(1)
	v_mfma_f32_16x16x32_bf16 v[40:43], v[134:137], v[176:179], v[40:43]
	s_add_u32 m0, s42, 0xf000
	s_nop 0
	global_load_lds_dwordx4 v71, s[100:101]
	s_add_u32 s98, s98, 0x80
	s_addc_u32 s99, s99, 0
	s_add_u32 s100, s100, 0x80
	s_addc_u32 s101, s101, 0
	ds_read_b128 v[204:207], v121 offset:38912
	s_waitcnt lgkmcnt(1)
	v_mfma_f32_16x16x32_bf16 v[28:31], v[168:171], v[176:179], v[28:31]
	s_waitcnt lgkmcnt(0)
	v_mfma_f32_16x16x32_bf16 v[12:15], v[204:207], v[176:179], v[12:15]
	v_mfma_f32_16x16x32_bf16 v[60:63], v[200:203], v[184:187], v[60:63]
	v_mfma_f32_16x16x32_bf16 v[44:47], v[134:137], v[184:187], v[44:47]
	v_mfma_f32_16x16x32_bf16 v[24:27], v[168:171], v[184:187], v[24:27]
	v_mfma_f32_16x16x32_bf16 v[8:11], v[204:207], v[184:187], v[8:11]
	v_mfma_f32_16x16x32_bf16 v[52:55], v[200:203], v[188:191], v[52:55]
	v_mfma_f32_16x16x32_bf16 v[36:39], v[134:137], v[188:191], v[36:39]
	v_mfma_f32_16x16x32_bf16 v[20:23], v[168:171], v[188:191], v[20:23]
	v_mfma_f32_16x16x32_bf16 v[4:7], v[204:207], v[188:191], v[4:7]
	v_mfma_f32_16x16x32_bf16 v[48:51], v[200:203], v[196:199], v[48:51]
	v_mfma_f32_16x16x32_bf16 v[32:35], v[134:137], v[196:199], v[32:35]
	v_mfma_f32_16x16x32_bf16 v[16:19], v[168:171], v[196:199], v[16:19]
	v_mfma_f32_16x16x32_bf16 v[0:3], v[204:207], v[196:199], v[0:3]
	s_setprio 0
	s_waitcnt vmcnt(0) lgkmcnt(0)
	s_barrier
	s_setprio 1
	ds_read_b128 v[84:87], v119 offset:49152
	ds_read_b128 v[88:91], v119 offset:51200
	ds_read_b128 v[56:59], v118 offset:16384
	ds_read_b128 v[72:75], v118 offset:18432
	ds_read_b128 v[76:79], v118 offset:20480
	ds_read_b128 v[92:95], v118 offset:22528
	s_waitcnt lgkmcnt(3)
	v_mfma_f32_16x16x32_bf16 v[64:67], v[84:87], v[56:59], v[64:67]
	ds_read_b128 v[134:137], v119 offset:53248
	v_mfma_f32_16x16x32_bf16 v[40:43], v[88:91], v[56:59], v[40:43]
	ds_read_b128 v[168:171], v119 offset:55296
	s_waitcnt lgkmcnt(1)
	v_mfma_f32_16x16x32_bf16 v[28:31], v[134:137], v[56:59], v[28:31]
	s_waitcnt lgkmcnt(0)
	v_mfma_f32_16x16x32_bf16 v[12:15], v[168:171], v[56:59], v[12:15]
	s_add_u32 m0, s42, 0x0
	s_nop 0
	global_load_lds_dwordx4 v68, s[98:99]
	ds_read_b128 v[176:179], v120 offset:16384
	v_mfma_f32_16x16x32_bf16 v[60:63], v[84:87], v[72:75], v[60:63]
	v_mfma_f32_16x16x32_bf16 v[44:47], v[88:91], v[72:75], v[44:47]
	s_add_u32 m0, s42, 0x1000
	s_nop 0
	global_load_lds_dwordx4 v69, s[98:99]
	ds_read_b128 v[184:187], v120 offset:18432
	v_mfma_f32_16x16x32_bf16 v[24:27], v[134:137], v[72:75], v[24:27]
	v_mfma_f32_16x16x32_bf16 v[8:11], v[168:171], v[72:75], v[8:11]
	s_add_u32 m0, s42, 0x2000
	s_nop 0
	global_load_lds_dwordx4 v70, s[98:99]
	ds_read_b128 v[188:191], v120 offset:20480
	v_mfma_f32_16x16x32_bf16 v[52:55], v[84:87], v[76:79], v[52:55]
	v_mfma_f32_16x16x32_bf16 v[36:39], v[88:91], v[76:79], v[36:39]
	s_add_u32 m0, s42, 0x3000
	s_nop 0
	global_load_lds_dwordx4 v71, s[98:99]
	ds_read_b128 v[196:199], v120 offset:22528
	v_mfma_f32_16x16x32_bf16 v[20:23], v[134:137], v[76:79], v[20:23]
	v_mfma_f32_16x16x32_bf16 v[4:7], v[168:171], v[76:79], v[4:7]
	s_add_u32 m0, s42, 0x8000
	s_nop 0
	global_load_lds_dwordx4 v68, s[100:101]
	ds_read_b128 v[200:203], v121 offset:49152
	v_mfma_f32_16x16x32_bf16 v[48:51], v[84:87], v[92:95], v[48:51]
	v_mfma_f32_16x16x32_bf16 v[32:35], v[88:91], v[92:95], v[32:35]
	s_add_u32 m0, s42, 0x9000
	s_nop 0
	global_load_lds_dwordx4 v69, s[100:101]
	ds_read_b128 v[204:207], v121 offset:51200
	v_mfma_f32_16x16x32_bf16 v[16:19], v[134:137], v[92:95], v[16:19]
	v_mfma_f32_16x16x32_bf16 v[0:3], v[168:171], v[92:95], v[0:3]
	s_add_u32 m0, s42, 0xa000
	s_nop 0
	global_load_lds_dwordx4 v70, s[100:101]
	ds_read_b128 v[134:137], v121 offset:53248
	s_waitcnt lgkmcnt(2)
	v_mfma_f32_16x16x32_bf16 v[64:67], v[200:203], v[176:179], v[64:67]
	s_waitcnt lgkmcnt(1)
	v_mfma_f32_16x16x32_bf16 v[40:43], v[204:207], v[176:179], v[40:43]
	s_add_u32 m0, s42, 0xb000
	s_nop 0
	global_load_lds_dwordx4 v71, s[100:101]
	s_add_u32 s98, s98, 0x80
	s_addc_u32 s99, s99, 0
	s_add_u32 s100, s100, 0x80
	s_addc_u32 s101, s101, 0
	ds_read_b128 v[168:171], v121 offset:55296
	s_waitcnt lgkmcnt(1)
	v_mfma_f32_16x16x32_bf16 v[28:31], v[134:137], v[176:179], v[28:31]
	s_waitcnt lgkmcnt(0)
	v_mfma_f32_16x16x32_bf16 v[12:15], v[168:171], v[176:179], v[12:15]
	v_mfma_f32_16x16x32_bf16 v[60:63], v[200:203], v[184:187], v[60:63]
	v_mfma_f32_16x16x32_bf16 v[44:47], v[204:207], v[184:187], v[44:47]
	v_mfma_f32_16x16x32_bf16 v[24:27], v[134:137], v[184:187], v[24:27]
	v_mfma_f32_16x16x32_bf16 v[8:11], v[168:171], v[184:187], v[8:11]
	v_mfma_f32_16x16x32_bf16 v[52:55], v[200:203], v[188:191], v[52:55]
	v_mfma_f32_16x16x32_bf16 v[36:39], v[204:207], v[188:191], v[36:39]
	v_mfma_f32_16x16x32_bf16 v[20:23], v[134:137], v[188:191], v[20:23]
	v_mfma_f32_16x16x32_bf16 v[4:7], v[168:171], v[188:191], v[4:7]
	v_mfma_f32_16x16x32_bf16 v[48:51], v[200:203], v[196:199], v[48:51]
	v_mfma_f32_16x16x32_bf16 v[32:35], v[204:207], v[196:199], v[32:35]
	v_mfma_f32_16x16x32_bf16 v[16:19], v[134:137], v[196:199], v[16:19]
	v_mfma_f32_16x16x32_bf16 v[0:3], v[168:171], v[196:199], v[0:3]
	s_setprio 0
	s_mov_b32 s40, s33
	s_waitcnt vmcnt(0) lgkmcnt(0)
	s_barrier
	s_cmp_lt_u32 s40, 16
	s_cbranch_scc1 .LBB0_1101
	s_waitcnt vmcnt(0)
	s_and_b32 s2, s9, 7
	s_and_b32 s26, s69, 7
	s_lshl_b32 s26, s26, 3
	s_or_b32 s2, s2, s26
	s_lshl_b32 s2, s2, 7
	s_lshr_b32 s26, s9, 3
	s_lshl_b32 s26, s26, 7
	v_readlane_b32 s42, v253, 0
	v_readlane_b32 s43, v253, 1
	s_load_dwordx2 s[98:99], s[42:43], 0x160
	s_load_dwordx2 s[100:101], s[42:43], 0x120
	v_and_b32_e32 v227, 15, v146
	v_bfe_u32 v228, v146, 7, 1
	v_lshl_add_u32 v227, v228, 6, v227
	v_add_u32_e32 v227, s2, v227
	v_bfe_u32 v228, v146, 4, 2
	v_lshlrev_b32_e32 v228, 2, v228
	v_bfe_u32 v218, v146, 6, 1
	v_lshl_add_u32 v228, v218, 6, v228
	v_add_u32_e32 v228, s26, v228
	v_lshlrev_b32_e32 v218, 2, v228
	v_lshl_add_u32 v96, v227, 12, v218
	v_add_u32_e32 v114, 0x10000, v96
	v_add_u32_e32 v115, 0x20000, v96
	v_add_u32_e32 v142, 0x30000, v96
	v_lshrrev_b32_e32 v214, 1, v96
	v_add_u32_e32 v214, 0xdc40000, v214
	v_lshrrev_b32_e32 v215, 1, v114
	v_add_u32_e32 v215, 0xdc40000, v215
	v_lshrrev_b32_e32 v216, 1, v115
	v_add_u32_e32 v216, 0xdc40000, v216
	v_lshrrev_b32_e32 v217, 1, v142
	v_add_u32_e32 v217, 0xdc40000, v217
	v_lshlrev_b32_e32 v222, 2, v227
	v_add_u32_e32 v222, 0xfa9a100, v222
	s_sub_u32 s33, s2, 0x1000
	s_lshr_b32 s33, s33, 10
	s_add_u32 s33, s33, 1
	s_cmp_lt_u32 s2, 0x1000
	s_cselect_b32 s33, 0, s33
	s_mul_i32 s33, s33, 0x3000
	v_add_u32_e32 v219, s33, v218
	v_add_u32_e32 v221, 0xf46e000, v219
	v_add_u32_e32 v219, 0xf460000, v219
	v_mbcnt_lo_u32_b32 v229, -1, 0
	v_mbcnt_hi_u32_b32 v229, -1, v229
	v_xor_b32_e32 v244, 32, v229
	v_xor_b32_e32 v229, 16, v229
	v_lshlrev_b32_e32 v244, 2, v244
	v_lshlrev_b32_e32 v229, 2, v229
	s_waitcnt lgkmcnt(0)
	s_mov_b64 s[42:43], s[98:99]
	global_load_dwordx4 v[160:163], v219, s[98:99]
	global_load_dwordx4 v[164:167], v219, s[98:99] offset:64
	global_load_dwordx4 v[168:171], v219, s[98:99] offset:128
	global_load_dwordx4 v[172:175], v219, s[98:99] offset:192
	global_load_dwordx4 v[176:179], v218, s[100:101]
	global_load_dwordx4 v[180:183], v218, s[100:101] offset:64
	global_load_dwordx4 v[184:187], v218, s[100:101] offset:128
	global_load_dwordx4 v[188:191], v218, s[100:101] offset:192
	global_load_dwordx4 v[192:195], v221, s[98:99]
	global_load_dwordx4 v[196:199], v221, s[98:99] offset:64
	global_load_dwordx4 v[200:203], v221, s[98:99] offset:128
	global_load_dwordx4 v[204:207], v221, s[98:99] offset:192
	global_load_dwordx4 v[56:59], v96, s[42:43]
	global_load_dwordx4 v[80:83], v114, s[42:43]
	global_load_dwordx4 v[98:101], v115, s[42:43]
	global_load_dwordx4 v[126:129], v142, s[42:43]
	global_load_dwordx4 v[68:71], v96, s[42:43] offset:64
	global_load_dwordx4 v[84:87], v114, s[42:43] offset:64
	global_load_dwordx4 v[102:105], v115, s[42:43] offset:64
	global_load_dwordx4 v[130:133], v142, s[42:43] offset:64
	global_load_dwordx4 v[72:75], v96, s[42:43] offset:128
	global_load_dwordx4 v[88:91], v114, s[42:43] offset:128
	global_load_dwordx4 v[106:109], v115, s[42:43] offset:128
	global_load_dwordx4 v[134:137], v142, s[42:43] offset:128
	global_load_dwordx4 v[76:79], v96, s[42:43] offset:192
	global_load_dwordx4 v[92:95], v114, s[42:43] offset:192
	global_load_dwordx4 v[110:113], v115, s[42:43] offset:192
	global_load_dwordx4 v[138:141], v142, s[42:43] offset:192
	v_mov_b32_e32 v223, 0
	v_mov_b32_e32 v224, 0
	v_mov_b32_e32 v225, 0
	v_mov_b32_e32 v226, 0
	s_waitcnt vmcnt(16)
	v_pk_add_f32 v[192:193], v[192:193], 1.0 op_sel_hi:[1,0]
	v_pk_add_f32 v[194:195], v[194:195], 1.0 op_sel_hi:[1,0]
	v_pk_mul_f32 v[192:193], v[176:177], v[192:193]
	v_pk_mul_f32 v[194:195], v[178:179], v[194:195]
	v_pk_add_f32 v[196:197], v[196:197], 1.0 op_sel_hi:[1,0]
	v_pk_add_f32 v[198:199], v[198:199], 1.0 op_sel_hi:[1,0]
	v_pk_mul_f32 v[196:197], v[180:181], v[196:197]
	v_pk_mul_f32 v[198:199], v[182:183], v[198:199]
	v_pk_add_f32 v[200:201], v[200:201], 1.0 op_sel_hi:[1,0]
	v_pk_add_f32 v[202:203], v[202:203], 1.0 op_sel_hi:[1,0]
	v_pk_mul_f32 v[200:201], v[184:185], v[200:201]
	v_pk_mul_f32 v[202:203], v[186:187], v[202:203]
	v_pk_add_f32 v[204:205], v[204:205], 1.0 op_sel_hi:[1,0]
	v_pk_add_f32 v[206:207], v[206:207], 1.0 op_sel_hi:[1,0]
	v_pk_mul_f32 v[204:205], v[188:189], v[204:205]
	v_pk_mul_f32 v[206:207], v[190:191], v[206:207]
	s_waitcnt vmcnt(15)
	v_pk_fma_f32 v[64:65], v[64:65], v[160:161], v[56:57]
	v_pk_fma_f32 v[66:67], v[66:67], v[162:163], v[58:59]
	global_store_dwordx4 v96, v[64:67], s[98:99]
	v_pk_mul_f32 v[56:57], v[192:193], v[64:65]
	v_pk_mul_f32 v[58:59], v[194:195], v[66:67]
	v_cvt_pk_bf16_f32 v56, v56, v57
	v_cvt_pk_bf16_f32 v57, v58, v59
	global_store_dwordx2 v214, v[56:57], s[98:99]
	v_pk_mul_f32 v[58:59], v[64:65], v[64:65]
	v_pk_fma_f32 v[58:59], v[66:67], v[66:67], v[58:59]
	v_add_f32_e32 v227, v58, v59
	v_add_f32_e32 v223, v223, v227
	s_waitcnt vmcnt(16)
	v_pk_fma_f32 v[60:61], v[60:61], v[160:161], v[80:81]
	v_pk_fma_f32 v[62:63], v[62:63], v[162:163], v[82:83]
	global_store_dwordx4 v114, v[60:63], s[98:99]
	v_pk_mul_f32 v[80:81], v[192:193], v[60:61]
	v_pk_mul_f32 v[82:83], v[194:195], v[62:63]
	v_cvt_pk_bf16_f32 v80, v80, v81
	v_cvt_pk_bf16_f32 v81, v82, v83
	global_store_dwordx2 v215, v[80:81], s[98:99]
	v_pk_mul_f32 v[82:83], v[60:61], v[60:61]
	v_pk_fma_f32 v[82:83], v[62:63], v[62:63], v[82:83]
	v_add_f32_e32 v227, v82, v83
	v_add_f32_e32 v224, v224, v227
	s_waitcnt vmcnt(17)
	v_pk_fma_f32 v[52:53], v[52:53], v[160:161], v[98:99]
	v_pk_fma_f32 v[54:55], v[54:55], v[162:163], v[100:101]
	global_store_dwordx4 v115, v[52:55], s[98:99]
	v_pk_mul_f32 v[98:99], v[192:193], v[52:53]
	v_pk_mul_f32 v[100:101], v[194:195], v[54:55]
	v_cvt_pk_bf16_f32 v98, v98, v99
	v_cvt_pk_bf16_f32 v99, v100, v101
	global_store_dwordx2 v216, v[98:99], s[98:99]
	v_pk_mul_f32 v[100:101], v[52:53], v[52:53]
	v_pk_fma_f32 v[100:101], v[54:55], v[54:55], v[100:101]
	v_add_f32_e32 v227, v100, v101
	v_add_f32_e32 v225, v225, v227
	s_waitcnt vmcnt(18)
	v_pk_fma_f32 v[48:49], v[48:49], v[160:161], v[126:127]
	v_pk_fma_f32 v[50:51], v[50:51], v[162:163], v[128:129]
	global_store_dwordx4 v142, v[48:51], s[98:99]
	v_pk_mul_f32 v[126:127], v[192:193], v[48:49]
	v_pk_mul_f32 v[128:129], v[194:195], v[50:51]
	v_cvt_pk_bf16_f32 v126, v126, v127
	v_cvt_pk_bf16_f32 v127, v128, v129
	global_store_dwordx2 v217, v[126:127], s[98:99]
	v_pk_mul_f32 v[128:129], v[48:49], v[48:49]
	v_pk_fma_f32 v[128:129], v[50:51], v[50:51], v[128:129]
	v_add_f32_e32 v227, v128, v129
	v_add_f32_e32 v226, v226, v227
	s_waitcnt vmcnt(19)
	v_pk_fma_f32 v[40:41], v[40:41], v[164:165], v[68:69]
	v_pk_fma_f32 v[42:43], v[42:43], v[166:167], v[70:71]
	global_store_dwordx4 v96, v[40:43], s[98:99] offset:64
	v_pk_mul_f32 v[68:69], v[196:197], v[40:41]
	v_pk_mul_f32 v[70:71], v[198:199], v[42:43]
	v_cvt_pk_bf16_f32 v68, v68, v69
	v_cvt_pk_bf16_f32 v69, v70, v71
	global_store_dwordx2 v214, v[68:69], s[98:99] offset:32
	v_pk_mul_f32 v[70:71], v[40:41], v[40:41]
	v_pk_fma_f32 v[70:71], v[42:43], v[42:43], v[70:71]
	v_add_f32_e32 v227, v70, v71
	v_add_f32_e32 v223, v223, v227
	s_waitcnt vmcnt(20)
	v_pk_fma_f32 v[44:45], v[44:45], v[164:165], v[84:85]
	v_pk_fma_f32 v[46:47], v[46:47], v[166:167], v[86:87]
	global_store_dwordx4 v114, v[44:47], s[98:99] offset:64
	v_pk_mul_f32 v[84:85], v[196:197], v[44:45]
	v_pk_mul_f32 v[86:87], v[198:199], v[46:47]
	v_cvt_pk_bf16_f32 v84, v84, v85
	v_cvt_pk_bf16_f32 v85, v86, v87
	global_store_dwordx2 v215, v[84:85], s[98:99] offset:32
	v_pk_mul_f32 v[86:87], v[44:45], v[44:45]
	v_pk_fma_f32 v[86:87], v[46:47], v[46:47], v[86:87]
	v_add_f32_e32 v227, v86, v87
	v_add_f32_e32 v224, v224, v227
	s_waitcnt vmcnt(21)
	v_pk_fma_f32 v[36:37], v[36:37], v[164:165], v[102:103]
	v_pk_fma_f32 v[38:39], v[38:39], v[166:167], v[104:105]
	global_store_dwordx4 v115, v[36:39], s[98:99] offset:64
	v_pk_mul_f32 v[102:103], v[196:197], v[36:37]
	v_pk_mul_f32 v[104:105], v[198:199], v[38:39]
	v_cvt_pk_bf16_f32 v102, v102, v103
	v_cvt_pk_bf16_f32 v103, v104, v105
	global_store_dwordx2 v216, v[102:103], s[98:99] offset:32
	v_pk_mul_f32 v[104:105], v[36:37], v[36:37]
	v_pk_fma_f32 v[104:105], v[38:39], v[38:39], v[104:105]
	v_add_f32_e32 v227, v104, v105
	v_add_f32_e32 v225, v225, v227
	s_waitcnt vmcnt(22)
	v_pk_fma_f32 v[32:33], v[32:33], v[164:165], v[130:131]
	v_pk_fma_f32 v[34:35], v[34:35], v[166:167], v[132:133]
	global_store_dwordx4 v142, v[32:35], s[98:99] offset:64
	v_pk_mul_f32 v[130:131], v[196:197], v[32:33]
	v_pk_mul_f32 v[132:133], v[198:199], v[34:35]
	v_cvt_pk_bf16_f32 v130, v130, v131
	v_cvt_pk_bf16_f32 v131, v132, v133
	global_store_dwordx2 v217, v[130:131], s[98:99] offset:32
	v_pk_mul_f32 v[132:133], v[32:33], v[32:33]
	v_pk_fma_f32 v[132:133], v[34:35], v[34:35], v[132:133]
	v_add_f32_e32 v227, v132, v133
	v_add_f32_e32 v226, v226, v227
	s_waitcnt vmcnt(23)
	v_pk_fma_f32 v[28:29], v[28:29], v[168:169], v[72:73]
	v_pk_fma_f32 v[30:31], v[30:31], v[170:171], v[74:75]
	global_store_dwordx4 v96, v[28:31], s[98:99] offset:128
	v_pk_mul_f32 v[72:73], v[200:201], v[28:29]
	v_pk_mul_f32 v[74:75], v[202:203], v[30:31]
	v_cvt_pk_bf16_f32 v72, v72, v73
	v_cvt_pk_bf16_f32 v73, v74, v75
	global_store_dwordx2 v214, v[72:73], s[98:99] offset:64
	v_pk_mul_f32 v[74:75], v[28:29], v[28:29]
	v_pk_fma_f32 v[74:75], v[30:31], v[30:31], v[74:75]
	v_add_f32_e32 v227, v74, v75
	v_add_f32_e32 v223, v223, v227
	s_waitcnt vmcnt(24)
	v_pk_fma_f32 v[24:25], v[24:25], v[168:169], v[88:89]
	v_pk_fma_f32 v[26:27], v[26:27], v[170:171], v[90:91]
	global_store_dwordx4 v114, v[24:27], s[98:99] offset:128
	v_pk_mul_f32 v[88:89], v[200:201], v[24:25]
	v_pk_mul_f32 v[90:91], v[202:203], v[26:27]
	v_cvt_pk_bf16_f32 v88, v88, v89
	v_cvt_pk_bf16_f32 v89, v90, v91
	global_store_dwordx2 v215, v[88:89], s[98:99] offset:64
	v_pk_mul_f32 v[90:91], v[24:25], v[24:25]
	v_pk_fma_f32 v[90:91], v[26:27], v[26:27], v[90:91]
	v_add_f32_e32 v227, v90, v91
	v_add_f32_e32 v224, v224, v227
	s_waitcnt vmcnt(25)
	v_pk_fma_f32 v[20:21], v[20:21], v[168:169], v[106:107]
	v_pk_fma_f32 v[22:23], v[22:23], v[170:171], v[108:109]
	global_store_dwordx4 v115, v[20:23], s[98:99] offset:128
	v_pk_mul_f32 v[106:107], v[200:201], v[20:21]
	v_pk_mul_f32 v[108:109], v[202:203], v[22:23]
	v_cvt_pk_bf16_f32 v106, v106, v107
	v_cvt_pk_bf16_f32 v107, v108, v109
	global_store_dwordx2 v216, v[106:107], s[98:99] offset:64
	v_pk_mul_f32 v[108:109], v[20:21], v[20:21]
	v_pk_fma_f32 v[108:109], v[22:23], v[22:23], v[108:109]
	v_add_f32_e32 v227, v108, v109
	v_add_f32_e32 v225, v225, v227
	s_waitcnt vmcnt(26)
	v_pk_fma_f32 v[16:17], v[16:17], v[168:169], v[134:135]
	v_pk_fma_f32 v[18:19], v[18:19], v[170:171], v[136:137]
	global_store_dwordx4 v142, v[16:19], s[98:99] offset:128
	v_pk_mul_f32 v[134:135], v[200:201], v[16:17]
	v_pk_mul_f32 v[136:137], v[202:203], v[18:19]
	v_cvt_pk_bf16_f32 v134, v134, v135
	v_cvt_pk_bf16_f32 v135, v136, v137
	global_store_dwordx2 v217, v[134:135], s[98:99] offset:64
	v_pk_mul_f32 v[136:137], v[16:17], v[16:17]
	v_pk_fma_f32 v[136:137], v[18:19], v[18:19], v[136:137]
	v_add_f32_e32 v227, v136, v137
	v_add_f32_e32 v226, v226, v227
	s_waitcnt vmcnt(27)
	v_pk_fma_f32 v[12:13], v[12:13], v[172:173], v[76:77]
	v_pk_fma_f32 v[14:15], v[14:15], v[174:175], v[78:79]
	global_store_dwordx4 v96, v[12:15], s[98:99] offset:192
	v_pk_mul_f32 v[76:77], v[204:205], v[12:13]
	v_pk_mul_f32 v[78:79], v[206:207], v[14:15]
	v_cvt_pk_bf16_f32 v76, v76, v77
	v_cvt_pk_bf16_f32 v77, v78, v79
	global_store_dwordx2 v214, v[76:77], s[98:99] offset:96
	v_pk_mul_f32 v[78:79], v[12:13], v[12:13]
	v_pk_fma_f32 v[78:79], v[14:15], v[14:15], v[78:79]
	v_add_f32_e32 v227, v78, v79
	v_add_f32_e32 v223, v223, v227
	s_waitcnt vmcnt(28)
	v_pk_fma_f32 v[8:9], v[8:9], v[172:173], v[92:93]
	v_pk_fma_f32 v[10:11], v[10:11], v[174:175], v[94:95]
	global_store_dwordx4 v114, v[8:11], s[98:99] offset:192
	v_pk_mul_f32 v[92:93], v[204:205], v[8:9]
	v_pk_mul_f32 v[94:95], v[206:207], v[10:11]
	v_cvt_pk_bf16_f32 v92, v92, v93
	v_cvt_pk_bf16_f32 v93, v94, v95
	global_store_dwordx2 v215, v[92:93], s[98:99] offset:96
	v_pk_mul_f32 v[94:95], v[8:9], v[8:9]
	v_pk_fma_f32 v[94:95], v[10:11], v[10:11], v[94:95]
	v_add_f32_e32 v227, v94, v95
	v_add_f32_e32 v224, v224, v227
	s_waitcnt vmcnt(29)
	v_pk_fma_f32 v[4:5], v[4:5], v[172:173], v[110:111]
	v_pk_fma_f32 v[6:7], v[6:7], v[174:175], v[112:113]
	global_store_dwordx4 v115, v[4:7], s[98:99] offset:192
	v_pk_mul_f32 v[110:111], v[204:205], v[4:5]
	v_pk_mul_f32 v[112:113], v[206:207], v[6:7]
	v_cvt_pk_bf16_f32 v110, v110, v111
	v_cvt_pk_bf16_f32 v111, v112, v113
	global_store_dwordx2 v216, v[110:111], s[98:99] offset:96
	v_pk_mul_f32 v[112:113], v[4:5], v[4:5]
	v_pk_fma_f32 v[112:113], v[6:7], v[6:7], v[112:113]
	v_add_f32_e32 v227, v112, v113
	v_add_f32_e32 v225, v225, v227
	s_waitcnt vmcnt(30)
	v_pk_fma_f32 v[0:1], v[0:1], v[172:173], v[138:139]
	v_pk_fma_f32 v[2:3], v[2:3], v[174:175], v[140:141]
	global_store_dwordx4 v142, v[0:3], s[98:99] offset:192
	v_pk_mul_f32 v[138:139], v[204:205], v[0:1]
	v_pk_mul_f32 v[140:141], v[206:207], v[2:3]
	v_cvt_pk_bf16_f32 v138, v138, v139
	v_cvt_pk_bf16_f32 v139, v140, v141
	global_store_dwordx2 v217, v[138:139], s[98:99] offset:96
	v_pk_mul_f32 v[140:141], v[0:1], v[0:1]
	v_pk_fma_f32 v[140:141], v[2:3], v[2:3], v[140:141]
	v_add_f32_e32 v227, v140, v141
	v_add_f32_e32 v226, v226, v227
	ds_bpermute_b32 v56, v229, v223
	ds_bpermute_b32 v80, v229, v224
	ds_bpermute_b32 v98, v229, v225
	ds_bpermute_b32 v126, v229, v226
	s_waitcnt lgkmcnt(0)
	v_add_f32_e32 v223, v223, v56
	v_add_f32_e32 v224, v224, v80
	v_add_f32_e32 v225, v225, v98
	v_add_f32_e32 v226, v226, v126
	ds_bpermute_b32 v56, v244, v223
	ds_bpermute_b32 v80, v244, v224
	ds_bpermute_b32 v98, v244, v225
	ds_bpermute_b32 v126, v244, v226
	s_waitcnt lgkmcnt(0)
	v_add_f32_e32 v223, v223, v56
	v_add_f32_e32 v224, v224, v80
	v_add_f32_e32 v225, v225, v98
	v_add_f32_e32 v226, v226, v126
	s_mov_b64 exec, 0xffff
	global_atomic_add_f32 v222, v223, s[98:99]
	global_atomic_add_f32 v222, v224, s[98:99] offset:64
	global_atomic_add_f32 v222, v225, s[98:99] offset:128
	global_atomic_add_f32 v222, v226, s[98:99] offset:192
	s_mov_b64 exec, -1
	s_mov_b32 s98, 0
	s_branch .LBB0_1099
